# v43 + softmax attention: P*V MFMAs interleaved k-step-major with the exp/sum/cvt groups (V fragments preloaded into spare VGPRs, rescale hoisted before exps), vgpr 256
# speedup vs baseline: 1.0007x; 1.0007x over previous
.LBB0_913:
	s_xor_b64 s[0:1], s[2:3], -1
	v_writelane_b32 v244, s0, 9
	v_mov_b32_e32 v2, v0
	v_readlane_b32 s6, v245, 14
	v_writelane_b32 v244, s1, 10
	s_and_b64 s[0:1], s[2:3], exec
	v_readlane_b32 s0, v244, 3
	v_readlane_b32 s1, v244, 4
	s_cselect_b32 s0, s1, s0
	v_readlane_b32 s2, v244, 5
	s_lshl_b32 s9, s0, 8
	s_lshl_b32 s1, s0, 2
	s_lshl_b32 s2, s2, 1
	s_lshl_b32 s0, s0, 16
	s_or_b32 s2, s0, s2
	v_mov_b32_e32 v12, v0
	v_readlane_b32 s7, v245, 15
	s_add_u32 s6, s6, s2
	s_addc_u32 s7, s7, 0
	v_readfirstlane_b32 s2, v12
	s_ashr_i32 s3, s2, 6
	s_and_b32 s2, s2, 0x3fffffc0
	s_lshl_b32 s2, s2, 2
	v_and_b32_e32 v13, 31, v12
	s_add_i32 s95, s2, 0
	s_lshl_b32 s2, s3, 5
	v_or_b32_e32 v4, s2, v13
	v_ashrrev_i32_e32 v5, 31, v4
	v_bfe_u32 v14, v12, 5, 1
	v_lshlrev_b64 v[4:5], 8, v[4:5]
	v_lshl_add_u64 v[4:5], s[6:7], 0, v[4:5]
	v_lshlrev_b32_e32 v2, 4, v14
	v_lshl_add_u64 v[4:5], v[4:5], 0, v[2:3]
	global_load_dwordx4 v[100:103], v[4:5], off offset:128
	global_load_dwordx4 v[104:107], v[4:5], off offset:160
	global_load_dwordx4 v[108:111], v[4:5], off offset:192
	global_load_dwordx4 v[112:115], v[4:5], off offset:224
	v_ashrrev_i32_e32 v5, 4, v12
	v_lshlrev_b32_e32 v6, 1, v5
	v_lshrrev_b32_e32 v7, 1, v5
	v_and_b32_e32 v4, 0x1fffff3, v5
	v_and_b32_e32 v6, 8, v6
	v_and_b32_e32 v7, 4, v7
	v_or3_b32 v4, v4, v6, v7
	v_and_b32_e32 v6, 15, v12
	v_bitop3_b32 v6, v5, v6, 7 bitop3:0x6c
	v_lshlrev_b32_e32 v6, 3, v6
	v_lshl_or_b32 v4, v4, 7, v6
	v_bfe_u32 v6, v12, 2, 2
	v_and_or_b32 v5, v5, s90, v6
	v_lshrrev_b32_e32 v6, 1, v12
	s_or_b32 s92, s1, 3
	s_add_i32 s95, s95, 0x20400
	v_and_b32_e32 v6, 8, v6
	s_lshl_b32 s3, s3, 10
	s_add_i32 s86, s2, s9
	s_lshl_b32 s1, s92, 14
	v_or3_b32 v5, v5, v6, v7
	v_lshlrev_b32_e32 v15, 3, v12
	s_add_u32 s80, s74, s1
	v_lshlrev_b32_e32 v5, 7, v5
	v_and_b32_e32 v6, 0x60, v12
	v_and_b32_e32 v7, 24, v15
	s_addc_u32 s81, s75, 0
	v_or3_b32 v6, v5, v6, v7
	v_ashrrev_i32_e32 v5, 31, v4
	s_add_u32 s96, s76, s1
	v_lshlrev_b64 v[4:5], 1, v[4:5]
	s_addc_u32 s97, s77, 0
	s_add_i32 s8, s3, 0
	v_lshl_add_u64 v[8:9], s[80:81], 0, v[4:5]
	v_ashrrev_i32_e32 v7, 31, v6
	s_add_i32 m0, s8, 0x1c000
	v_lshlrev_b64 v[6:7], 1, v[6:7]
	global_load_lds_dwordx4 v[8:9], off
	v_lshl_add_u64 v[8:9], v[8:9], 0, s[84:85]
	s_add_i32 m0, s8, 0x1e000
	v_lshl_add_u64 v[10:11], s[96:97], 0, v[6:7]
	global_load_lds_dwordx4 v[8:9], off
	s_add_i32 m0, s8, 0xc000
	s_or_b32 s1, s0, 0x8000
	global_load_lds_dwordx4 v[10:11], off
	s_add_i32 m0, s8, 0xe000
	s_add_u32 s82, s74, s1
	s_addc_u32 s83, s75, 0
	v_lshl_add_u64 v[8:9], v[10:11], 0, s[84:85]
	s_add_u32 s88, s76, s1
	global_load_lds_dwordx4 v[8:9], off
	v_lshl_add_u64 v[8:9], s[82:83], 0, v[4:5]
	s_addc_u32 s89, s77, 0
	s_add_i32 m0, s8, 0x18000
	v_lshl_add_u64 v[10:11], s[88:89], 0, v[6:7]
	global_load_lds_dwordx4 v[8:9], off
	v_lshl_add_u64 v[8:9], v[8:9], 0, s[84:85]
	s_add_i32 m0, s8, 0x1a000
	v_lshl_add_u64 v[148:149], s[74:75], 0, v[4:5]
	global_load_lds_dwordx4 v[8:9], off
	s_add_i32 m0, s8, 0x8000
	v_lshl_add_u64 v[8:9], v[10:11], 0, s[84:85]
	global_load_lds_dwordx4 v[10:11], off
	s_add_i32 m0, s8, 0xa000
	v_lshlrev_b32_e32 v5, 4, v12
	global_load_lds_dwordx4 v[8:9], off
	v_lshl_add_u64 v[150:151], s[76:77], 0, v[6:7]
	v_lshlrev_b32_e32 v4, 1, v12
	v_and_b32_e32 v6, 0xc0, v5
	v_and_b32_e32 v5, 0x70, v5
	s_movk_i32 s3, 0x80
	v_and_b32_e32 v4, 32, v4
	v_bitop3_b32 v153, v2, v5, s3 bitop3:0x36
	s_movk_i32 s3, 0xa0
	v_and_or_b32 v4, v15, s93, v4
	v_bitop3_b32 v155, v2, v5, s3 bitop3:0x36
	s_movk_i32 s3, 0xc0
	s_addk_i32 s2, 0xff40
	v_and_b32_e32 v8, 63, v12
	v_lshlrev_b32_e32 v9, 3, v14
	s_waitcnt vmcnt(0)
	v_bitop3_b32 v156, v2, v5, s3 bitop3:0x36
	s_movk_i32 s3, 0xe0
	v_add3_u32 v158, v6, 0, v4
	v_or_b32_e32 v4, s2, v13
	v_mov_b32_e32 v18, v3
	v_mov_b32_e32 v19, v3
	v_lshlrev_b32_e32 v152, 8, v13
	v_bitop3_b32 v157, v2, v5, s3 bitop3:0x36
	v_cmp_gt_u32_e64 s[10:11], 32, v8
	v_lshl_add_u32 v154, v13, 2, s95
	v_sub_u32_e32 v159, v4, v9
	v_mov_b32_e32 v4, v3
	v_mov_b32_e32 v5, v3
	v_mov_b32_e32 v6, v3
	v_mov_b32_e32 v7, v3
	v_mov_b32_e32 v8, v3
	v_mov_b32_e32 v9, v3
	v_mov_b32_e32 v10, v3
	v_mov_b32_e32 v11, v3
	v_mov_b32_e32 v12, v3
	v_mov_b32_e32 v13, v3
	v_mov_b32_e32 v14, v3
	v_mov_b32_e32 v15, v3
	v_mov_b32_e32 v16, v3
	v_mov_b32_e32 v17, v3
	v_mov_b64_e32 v[34:35], v[18:19]
	v_mov_b64_e32 v[50:51], v[18:19]
	v_mov_b64_e32 v[66:67], v[18:19]
	s_add_i32 s1, s8, 0x10000
	s_or_b32 s90, s86, 31
	v_mov_b32_e32 v161, 0
	v_mov_b32_e32 v160, 0xf149f2ca
	v_mov_b32_e32 v240, 0xf149f2ca
	v_mov_b64_e32 v[184:185], 0
	v_mov_b64_e32 v[186:187], 0
	v_mov_b64_e32 v[188:189], 0
	v_mov_b64_e32 v[190:191], 0
	v_mov_b64_e32 v[192:193], 0
	v_mov_b64_e32 v[194:195], 0
	v_mov_b64_e32 v[196:197], 0
	v_mov_b64_e32 v[198:199], 0
	s_mov_b32 s2, s9
	s_mov_b32 s33, s0
	v_mov_b64_e32 v[32:33], v[16:17]
	v_mov_b64_e32 v[30:31], v[14:15]
	v_mov_b64_e32 v[28:29], v[12:13]
	v_mov_b64_e32 v[26:27], v[10:11]
	v_mov_b64_e32 v[24:25], v[8:9]
	v_mov_b64_e32 v[22:23], v[6:7]
	v_mov_b64_e32 v[20:21], v[4:5]
	v_mov_b64_e32 v[48:49], v[16:17]
	v_mov_b64_e32 v[46:47], v[14:15]
	v_mov_b64_e32 v[44:45], v[12:13]
	v_mov_b64_e32 v[42:43], v[10:11]
	v_mov_b64_e32 v[40:41], v[8:9]
	v_mov_b64_e32 v[38:39], v[6:7]
	v_mov_b64_e32 v[36:37], v[4:5]
	v_mov_b64_e32 v[64:65], v[16:17]
	v_mov_b64_e32 v[62:63], v[14:15]
	v_mov_b64_e32 v[60:61], v[12:13]
	v_mov_b64_e32 v[58:59], v[10:11]
	v_mov_b64_e32 v[56:57], v[8:9]
	v_mov_b64_e32 v[54:55], v[6:7]
	v_mov_b64_e32 v[52:53], v[4:5]
	s_mov_b32 s94, s92
	s_waitcnt vmcnt(0) lgkmcnt(0)
	s_barrier
	s_branch .LBB0_917
.LBB0_916:
	s_waitcnt vmcnt(0)
	s_add_i32 s94, s94, -2
	s_addk_i32 s33, 0x8000
	s_addk_i32 s2, 0xff80
	v_add_u32_e32 v159, 0x80, v159
	s_and_b64 vcc, exec, s[78:79]
	s_waitcnt vmcnt(0) lgkmcnt(0)
	s_barrier
	s_cbranch_vccnz .LBB0_937

.LBB0_921:
	s_add_i32 s4, s33, 0xc000
	s_and_b32 s4, s4, 0xc000
	s_add_i32 s12, s4, 0
	s_add_i32 s12, s12, 0x10000
	v_add_u32_e32 v76, s12, v152
	v_add_u32_e32 v77, v76, v153
	ds_read_b128 v[68:71], v77 offset:0
	ds_read_b128 v[72:75], v77 offset:0x2000
	v_add_u32_e32 v77, v76, v155
	ds_read_b128 v[116:119], v77 offset:0
	ds_read_b128 v[120:123], v77 offset:0x2000
	v_add_u32_e32 v77, v76, v156
	ds_read_b128 v[124:127], v77 offset:0
	ds_read_b128 v[128:131], v77 offset:0x2000
	v_add_u32_e32 v76, v76, v157
	ds_read_b128 v[132:135], v76 offset:0
	ds_read_b128 v[136:139], v76 offset:0x2000
	s_waitcnt lgkmcnt(4)
	s_add_i32 s3, s2, 0xff
	s_cmp_le_u32 s3, s86
	v_mfma_f32_32x32x16_bf16 v[84:99], v[68:71], v[100:103], v[184:199]
	v_mfma_f32_32x32x16_bf16 v[84:99], v[116:119], v[104:107], v[84:99]
	v_mfma_f32_32x32x16_bf16 v[68:83], v[72:75], v[100:103], v[184:199]
	v_mfma_f32_32x32x16_bf16 v[68:83], v[120:123], v[104:107], v[68:83]
	s_waitcnt lgkmcnt(0)
	v_mfma_f32_32x32x16_bf16 v[84:99], v[124:127], v[108:111], v[84:99]
	v_mfma_f32_32x32x16_bf16 v[84:99], v[132:135], v[112:115], v[84:99]
	v_mfma_f32_32x32x16_bf16 v[68:83], v[128:131], v[108:111], v[68:83]
	v_mfma_f32_32x32x16_bf16 v[68:83], v[136:139], v[112:115], v[68:83]
	v_add_u32_e32 v162, s4, v158
	ds_read_b64_tr_b16 v[144:145], v162 offset:0
	ds_read_b64_tr_b16 v[146:147], v162 offset:0x800
	ds_read_b64_tr_b16 v[140:141], v162 offset:0x1000
	ds_read_b64_tr_b16 v[142:143], v162 offset:0x1800
	ds_read_b64_tr_b16 v[136:137], v162 offset:0x2000
	ds_read_b64_tr_b16 v[138:139], v162 offset:0x2800
	ds_read_b64_tr_b16 v[132:133], v162 offset:0x3000
	ds_read_b64_tr_b16 v[134:135], v162 offset:0x3800
	ds_read_b64_tr_b16 v[128:129], v162 offset:0x200
	ds_read_b64_tr_b16 v[130:131], v162 offset:0xa00
	ds_read_b64_tr_b16 v[124:125], v162 offset:0x1200
	ds_read_b64_tr_b16 v[126:127], v162 offset:0x1a00
	ds_read_b64_tr_b16 v[120:121], v162 offset:0x2200
	ds_read_b64_tr_b16 v[122:123], v162 offset:0x2a00
	ds_read_b64_tr_b16 v[116:117], v162 offset:0x3200
	ds_read_b64_tr_b16 v[118:119], v162 offset:0x3a00
	ds_read_b64_tr_b16 v[206:207], v162 offset:0x400
	ds_read_b64_tr_b16 v[208:209], v162 offset:0xc00
	ds_read_b64_tr_b16 v[212:213], v162 offset:0x1400
	ds_read_b64_tr_b16 v[214:215], v162 offset:0x1c00
	ds_read_b64_tr_b16 v[220:221], v162 offset:0x2400
	ds_read_b64_tr_b16 v[222:223], v162 offset:0x2c00
	ds_read_b64_tr_b16 v[224:225], v162 offset:0x3400
	ds_read_b64_tr_b16 v[226:227], v162 offset:0x3c00
	ds_read_b64_tr_b16 v[228:229], v162 offset:0x600
	ds_read_b64_tr_b16 v[230:231], v162 offset:0xe00
	ds_read_b64_tr_b16 v[232:233], v162 offset:0x1600
	ds_read_b64_tr_b16 v[234:235], v162 offset:0x1e00
	ds_read_b64_tr_b16 v[236:237], v162 offset:0x2600
	ds_read_b64_tr_b16 v[238:239], v162 offset:0x2e00
	ds_read_b64_tr_b16 v[248:249], v162 offset:0x3600
	ds_read_b64_tr_b16 v[250:251], v162 offset:0x3e00
	s_cbranch_scc1 .LBB0_923
	v_cmp_gt_i32_e64 s[70:71], 22, v159
	v_cmp_gt_i32_e64 s[72:73], 23, v159
	v_cmp_gt_i32_e64 s[68:69], 21, v159
	s_and_b64 s[70:71], s[72:73], s[70:71]
	v_cmp_gt_i32_e64 s[66:67], 20, v159
	s_and_b64 s[68:69], s[70:71], s[68:69]
	v_cmp_gt_i32_e64 s[64:65], 19, v159
	s_and_b64 s[66:67], s[68:69], s[66:67]
	v_cmp_gt_i32_e64 s[62:63], 18, v159
	s_and_b64 s[64:65], s[66:67], s[64:65]
	v_cmp_gt_i32_e64 s[60:61], 17, v159
	s_and_b64 s[62:63], s[64:65], s[62:63]
	v_cmp_gt_i32_e64 s[58:59], 16, v159
	s_and_b64 s[60:61], s[62:63], s[60:61]
	v_cmp_gt_i32_e64 s[56:57], 7, v159
	s_and_b64 s[58:59], s[60:61], s[58:59]
	v_cmp_gt_i32_e64 s[54:55], 6, v159
	s_and_b64 s[56:57], s[58:59], s[56:57]
	v_cmp_gt_i32_e64 s[52:53], 5, v159
	s_and_b64 s[54:55], s[56:57], s[54:55]
	v_cmp_gt_i32_e64 s[50:51], 4, v159
	s_and_b64 s[52:53], s[54:55], s[52:53]
	v_cmp_gt_i32_e64 s[48:49], 3, v159
	s_and_b64 s[50:51], s[52:53], s[50:51]
	v_cmp_gt_i32_e64 s[46:47], 2, v159
	s_and_b64 s[48:49], s[50:51], s[48:49]
	v_cmp_gt_i32_e64 s[44:45], 1, v159
	s_and_b64 s[46:47], s[48:49], s[46:47]
	v_cmp_gt_i32_e64 s[42:43], 0, v159
	s_and_b64 s[44:45], s[46:47], s[44:45]
	s_and_b64 s[42:43], s[44:45], s[42:43]
	v_cmp_gt_i32_e64 s[40:41], 54, v159
	v_cndmask_b32_e64 v84, v84, v204, s[42:43]
	v_cmp_gt_i32_e64 s[42:43], 55, v159
	v_cmp_gt_i32_e64 s[38:39], 53, v159
	s_and_b64 s[40:41], s[42:43], s[40:41]
	v_cmp_gt_i32_e64 s[36:37], 52, v159
	s_and_b64 s[38:39], s[40:41], s[38:39]
	v_cmp_gt_i32_e64 s[34:35], 51, v159
	s_and_b64 s[36:37], s[38:39], s[36:37]
	v_cmp_gt_i32_e64 s[30:31], 50, v159
	s_and_b64 s[34:35], s[36:37], s[34:35]
	v_cmp_gt_i32_e64 s[28:29], 49, v159
	s_and_b64 s[30:31], s[34:35], s[30:31]
	v_cmp_gt_i32_e64 s[26:27], 48, v159
	s_and_b64 s[28:29], s[30:31], s[28:29]
	v_cmp_gt_i32_e64 s[24:25], 39, v159
	s_and_b64 s[26:27], s[28:29], s[26:27]
	v_cmp_gt_i32_e64 s[22:23], 38, v159
	s_and_b64 s[24:25], s[26:27], s[24:25]
	v_cmp_gt_i32_e64 s[20:21], 37, v159
	s_and_b64 s[22:23], s[24:25], s[22:23]
	v_cmp_gt_i32_e64 s[18:19], 36, v159
	s_and_b64 s[20:21], s[22:23], s[20:21]
	v_cmp_gt_i32_e64 s[16:17], 35, v159
	s_and_b64 s[18:19], s[20:21], s[18:19]
	v_cmp_gt_i32_e64 s[14:15], 34, v159
	s_and_b64 s[16:17], s[18:19], s[16:17]
	v_cmp_gt_i32_e64 s[12:13], 33, v159
	s_and_b64 s[14:15], s[16:17], s[14:15]
	v_cmp_gt_i32_e32 vcc, 32, v159
	s_and_b64 s[12:13], s[14:15], s[12:13]
	s_and_b64 vcc, s[12:13], vcc
	v_cndmask_b32_e64 v99, v99, v204, s[72:73]
	v_cndmask_b32_e64 v98, v98, v204, s[70:71]
	v_cndmask_b32_e64 v97, v97, v204, s[68:69]
	v_cndmask_b32_e64 v96, v96, v204, s[66:67]
	v_cndmask_b32_e64 v95, v95, v204, s[64:65]
	v_cndmask_b32_e64 v94, v94, v204, s[62:63]
	v_cndmask_b32_e64 v93, v93, v204, s[60:61]
	v_cndmask_b32_e64 v92, v92, v204, s[58:59]
	v_cndmask_b32_e64 v91, v91, v204, s[56:57]
	v_cndmask_b32_e64 v90, v90, v204, s[54:55]
	v_cndmask_b32_e64 v89, v89, v204, s[52:53]
	v_cndmask_b32_e64 v88, v88, v204, s[50:51]
	v_cndmask_b32_e64 v87, v87, v204, s[48:49]
	v_cndmask_b32_e64 v86, v86, v204, s[46:47]
	v_cndmask_b32_e64 v85, v85, v204, s[44:45]
	v_cndmask_b32_e64 v83, v83, v204, s[42:43]
	v_cndmask_b32_e64 v82, v82, v204, s[40:41]
	v_cndmask_b32_e64 v81, v81, v204, s[38:39]
	v_cndmask_b32_e64 v80, v80, v204, s[36:37]
	v_cndmask_b32_e64 v79, v79, v204, s[34:35]
	v_cndmask_b32_e64 v78, v78, v204, s[30:31]
	v_cndmask_b32_e64 v77, v77, v204, s[28:29]
	v_cndmask_b32_e64 v76, v76, v204, s[26:27]
	v_cndmask_b32_e64 v75, v75, v204, s[24:25]
	v_cndmask_b32_e64 v74, v74, v204, s[22:23]
	v_cndmask_b32_e64 v73, v73, v204, s[20:21]
	v_cndmask_b32_e64 v72, v72, v204, s[18:19]
	v_cndmask_b32_e64 v71, v71, v204, s[16:17]
	v_cndmask_b32_e64 v70, v70, v204, s[14:15]
	v_cndmask_b32_e64 v69, v69, v204, s[12:13]
	v_cndmask_b32_e32 v68, v68, v204, vcc

.LBB0_924:
	v_cmp_gt_f32_e32 vcc, 1.0, v163
	s_cbranch_vccz .Lfa_b_1
	s_and_saveexec_b64 s[12:13], s[10:11]
	ds_write_b32 v154, v163 offset:128
	s_or_b64 exec, exec, s[12:13]
	s_waitcnt lgkmcnt(0)
	v_add_u32_e32 v178, s95, v2
	ds_read_b128 v[166:169], v178 offset:224
	ds_read_b128 v[170:173], v178 offset:192
	ds_read_b128 v[174:177], v178 offset:160
	ds_read_b128 v[178:181], v178 offset:128
	s_waitcnt lgkmcnt(0)
	s_waitcnt lgkmcnt(0)
	v_pk_mul_f32 v[64:65], v[166:167], v[64:65]
	v_pk_mul_f32 v[60:61], v[170:171], v[60:61]
	v_pk_mul_f32 v[56:57], v[174:175], v[56:57]
	v_pk_mul_f32 v[66:67], v[168:169], v[66:67]
	v_pk_mul_f32 v[62:63], v[172:173], v[62:63]
	v_pk_mul_f32 v[58:59], v[176:177], v[58:59]
	v_pk_mul_f32 v[54:55], v[180:181], v[54:55]
	v_pk_mul_f32 v[52:53], v[178:179], v[52:53]
	v_pk_mul_f32 v[48:49], v[166:167], v[48:49]
	v_pk_mul_f32 v[44:45], v[170:171], v[44:45]
	v_pk_mul_f32 v[40:41], v[174:175], v[40:41]
	v_pk_mul_f32 v[50:51], v[168:169], v[50:51]
	v_pk_mul_f32 v[46:47], v[172:173], v[46:47]
	v_pk_mul_f32 v[42:43], v[176:177], v[42:43]
	v_pk_mul_f32 v[38:39], v[180:181], v[38:39]
	v_pk_mul_f32 v[36:37], v[178:179], v[36:37]
	v_pk_mul_f32 v[32:33], v[166:167], v[32:33]
	v_pk_mul_f32 v[28:29], v[170:171], v[28:29]
	v_pk_mul_f32 v[24:25], v[174:175], v[24:25]
	v_pk_mul_f32 v[34:35], v[168:169], v[34:35]
	v_pk_mul_f32 v[30:31], v[172:173], v[30:31]
	v_pk_mul_f32 v[26:27], v[176:177], v[26:27]
	v_pk_mul_f32 v[22:23], v[180:181], v[22:23]
	v_pk_mul_f32 v[20:21], v[178:179], v[20:21]
	v_pk_mul_f32 v[16:17], v[166:167], v[16:17]
	v_pk_mul_f32 v[12:13], v[170:171], v[12:13]
	v_pk_mul_f32 v[8:9], v[174:175], v[8:9]
	v_pk_mul_f32 v[18:19], v[168:169], v[18:19]
	v_pk_mul_f32 v[14:15], v[172:173], v[14:15]
	v_pk_mul_f32 v[10:11], v[176:177], v[10:11]
	v_pk_mul_f32 v[6:7], v[180:181], v[6:7]
	v_pk_mul_f32 v[4:5], v[178:179], v[4:5]
.Lfa_b_1:
	v_mov_b32_e32 v243, v83
	v_exp_f32_e32 v164, v84
	v_exp_f32_e32 v85, v85
	v_exp_f32_e32 v86, v86
	v_exp_f32_e32 v87, v87
	v_exp_f32_e32 v88, v88
	v_exp_f32_e32 v89, v89
	v_exp_f32_e32 v90, v90
	v_exp_f32_e32 v165, v91
	v_add_f32_e32 v83, 0, v164
	v_add_f32_e32 v83, v85, v83
	v_add_f32_e32 v83, v86, v83
	v_add_f32_e32 v83, v87, v83
	v_cvt_pk_bf16_f32 v166, v164, v85
	v_cvt_pk_bf16_f32 v167, v86, v87
	v_cvt_pk_bf16_f32 v168, v88, v89
	v_cvt_pk_bf16_f32 v169, v90, v165
	v_exp_f32_e32 v91, v92
	v_exp_f32_e32 v92, v93
	s_waitcnt lgkmcnt(0)
	v_mfma_f32_32x32x16_bf16 v[52:67], v[166:169], v[144:147], v[52:67]
	v_mfma_f32_32x32x16_bf16 v[36:51], v[166:169], v[128:131], v[36:51]
	v_mfma_f32_32x32x16_bf16 v[20:35], v[166:169], v[206:209], v[20:35]
	v_mfma_f32_32x32x16_bf16 v[4:19], v[166:169], v[228:231], v[4:19]
	v_exp_f32_e32 v93, v94
	v_exp_f32_e32 v94, v95
	v_exp_f32_e32 v95, v96
	v_exp_f32_e32 v96, v97
	v_exp_f32_e32 v97, v98
	v_exp_f32_e32 v98, v99
	v_add_f32_e32 v83, v88, v83
	v_add_f32_e32 v83, v89, v83
	v_add_f32_e32 v83, v90, v83
	v_add_f32_e32 v83, v165, v83
	v_add_f32_e32 v83, v91, v83
	v_add_f32_e32 v83, v92, v83
	v_add_f32_e32 v83, v93, v83
	v_add_f32_e32 v83, v94, v83
	v_cvt_pk_bf16_f32 v86, v91, v92
	v_cvt_pk_bf16_f32 v87, v93, v94
	v_cvt_pk_bf16_f32 v88, v95, v96
	v_cvt_pk_bf16_f32 v89, v97, v98
	v_exp_f32_e32 v68, v68
	v_exp_f32_e32 v69, v69
	v_mfma_f32_32x32x16_bf16 v[52:67], v[86:89], v[140:143], v[52:67]
	v_mfma_f32_32x32x16_bf16 v[36:51], v[86:89], v[124:127], v[36:51]
	v_mfma_f32_32x32x16_bf16 v[20:35], v[86:89], v[212:215], v[20:35]
	v_mfma_f32_32x32x16_bf16 v[4:19], v[86:89], v[232:235], v[4:19]
	v_exp_f32_e32 v70, v70
	v_exp_f32_e32 v71, v71
	v_exp_f32_e32 v72, v72
	v_exp_f32_e32 v73, v73
	v_exp_f32_e32 v74, v74
	v_exp_f32_e32 v84, v75
	v_add_f32_e32 v83, v95, v83
	v_add_f32_e32 v83, v96, v83
	v_add_f32_e32 v83, v97, v83
	v_add_f32_e32 v83, v98, v83
	v_add_f32_e32 v83, v68, v83
	v_add_f32_e32 v83, v69, v83
	v_add_f32_e32 v83, v70, v83
	v_add_f32_e32 v83, v71, v83
	v_cvt_pk_bf16_f32 v68, v68, v69
	v_cvt_pk_bf16_f32 v69, v70, v71
	v_cvt_pk_bf16_f32 v70, v72, v73
	v_cvt_pk_bf16_f32 v71, v74, v84
	v_exp_f32_e32 v75, v76
	v_exp_f32_e32 v76, v77
	v_mfma_f32_32x32x16_bf16 v[52:67], v[68:71], v[136:139], v[52:67]
	v_mfma_f32_32x32x16_bf16 v[36:51], v[68:71], v[120:123], v[36:51]
	v_mfma_f32_32x32x16_bf16 v[20:35], v[68:71], v[220:223], v[20:35]
	v_mfma_f32_32x32x16_bf16 v[4:19], v[68:71], v[236:239], v[4:19]
	v_exp_f32_e32 v77, v78
	v_exp_f32_e32 v78, v79
	v_exp_f32_e32 v79, v80
	v_exp_f32_e32 v80, v81
	v_exp_f32_e32 v81, v82
	v_exp_f32_e32 v82, v243
	v_add_f32_e32 v83, v72, v83
	v_add_f32_e32 v83, v73, v83
	v_add_f32_e32 v83, v74, v83
	v_add_f32_e32 v83, v84, v83
	v_add_f32_e32 v83, v75, v83
	v_add_f32_e32 v83, v76, v83
	v_add_f32_e32 v83, v77, v83
	v_add_f32_e32 v83, v78, v83
	v_add_f32_e32 v83, v79, v83
	v_add_f32_e32 v83, v80, v83
	v_add_f32_e32 v83, v81, v83
	v_add_f32_e32 v83, v82, v83
	v_cvt_pk_bf16_f32 v72, v75, v76
	v_cvt_pk_bf16_f32 v73, v77, v78
	v_cvt_pk_bf16_f32 v74, v79, v80
	v_cvt_pk_bf16_f32 v75, v81, v82
	v_mov_b32_e32 v99, v83
	s_nop 1
	v_permlane32_swap_b32_e32 v83, v99
	v_mfma_f32_32x32x16_bf16 v[52:67], v[72:75], v[132:135], v[52:67]
	v_mfma_f32_32x32x16_bf16 v[36:51], v[72:75], v[116:119], v[36:51]
	v_mfma_f32_32x32x16_bf16 v[20:35], v[72:75], v[224:227], v[20:35]
	v_mfma_f32_32x32x16_bf16 v[4:19], v[72:75], v[248:251], v[4:19]
	v_add_f32_e32 v99, v83, v99
	v_fmac_f32_e32 v99, v161, v163
	v_mov_b32_e32 v161, v99
	s_add_i32 s3, s2, 0x80
	s_cmp_gt_i32 s3, s90
	s_cbranch_scc1 .LBB0_916
.LBB0_929:
	s_add_i32 s4, s33, 0x8000
	s_and_b32 s4, s4, 0xc000
	s_add_i32 s12, s4, 0
	s_add_i32 s12, s12, 0x10000
	v_add_u32_e32 v76, s12, v152
	v_add_u32_e32 v77, v76, v153
	ds_read_b128 v[68:71], v77 offset:0
	ds_read_b128 v[72:75], v77 offset:0x2000
	v_add_u32_e32 v77, v76, v155
	ds_read_b128 v[116:119], v77 offset:0
	ds_read_b128 v[120:123], v77 offset:0x2000
	v_add_u32_e32 v77, v76, v156
	ds_read_b128 v[124:127], v77 offset:0
	ds_read_b128 v[128:131], v77 offset:0x2000
	v_add_u32_e32 v76, v76, v157
	ds_read_b128 v[132:135], v76 offset:0
	ds_read_b128 v[136:139], v76 offset:0x2000
	s_waitcnt lgkmcnt(4)
	s_add_i32 s3, s2, 0xbf
	s_cmp_le_i32 s3, s86
	v_mfma_f32_32x32x16_bf16 v[84:99], v[68:71], v[100:103], v[184:199]
	v_mfma_f32_32x32x16_bf16 v[84:99], v[116:119], v[104:107], v[84:99]
	v_mfma_f32_32x32x16_bf16 v[68:83], v[72:75], v[100:103], v[184:199]
	v_mfma_f32_32x32x16_bf16 v[68:83], v[120:123], v[104:107], v[68:83]
	s_waitcnt lgkmcnt(0)
	v_mfma_f32_32x32x16_bf16 v[84:99], v[124:127], v[108:111], v[84:99]
	v_mfma_f32_32x32x16_bf16 v[84:99], v[132:135], v[112:115], v[84:99]
	v_mfma_f32_32x32x16_bf16 v[68:83], v[128:131], v[108:111], v[68:83]
	v_mfma_f32_32x32x16_bf16 v[68:83], v[136:139], v[112:115], v[68:83]
	v_add_u32_e32 v162, s4, v158
	ds_read_b64_tr_b16 v[144:145], v162 offset:0
	ds_read_b64_tr_b16 v[146:147], v162 offset:0x800
	ds_read_b64_tr_b16 v[140:141], v162 offset:0x1000
	ds_read_b64_tr_b16 v[142:143], v162 offset:0x1800
	ds_read_b64_tr_b16 v[136:137], v162 offset:0x2000
	ds_read_b64_tr_b16 v[138:139], v162 offset:0x2800
	ds_read_b64_tr_b16 v[132:133], v162 offset:0x3000
	ds_read_b64_tr_b16 v[134:135], v162 offset:0x3800
	ds_read_b64_tr_b16 v[128:129], v162 offset:0x200
	ds_read_b64_tr_b16 v[130:131], v162 offset:0xa00
	ds_read_b64_tr_b16 v[124:125], v162 offset:0x1200
	ds_read_b64_tr_b16 v[126:127], v162 offset:0x1a00
	ds_read_b64_tr_b16 v[120:121], v162 offset:0x2200
	ds_read_b64_tr_b16 v[122:123], v162 offset:0x2a00
	ds_read_b64_tr_b16 v[116:117], v162 offset:0x3200
	ds_read_b64_tr_b16 v[118:119], v162 offset:0x3a00
	ds_read_b64_tr_b16 v[206:207], v162 offset:0x400
	ds_read_b64_tr_b16 v[208:209], v162 offset:0xc00
	ds_read_b64_tr_b16 v[212:213], v162 offset:0x1400
	ds_read_b64_tr_b16 v[214:215], v162 offset:0x1c00
	ds_read_b64_tr_b16 v[220:221], v162 offset:0x2400
	ds_read_b64_tr_b16 v[222:223], v162 offset:0x2c00
	ds_read_b64_tr_b16 v[224:225], v162 offset:0x3400
	ds_read_b64_tr_b16 v[226:227], v162 offset:0x3c00
	ds_read_b64_tr_b16 v[228:229], v162 offset:0x600
	ds_read_b64_tr_b16 v[230:231], v162 offset:0xe00
	ds_read_b64_tr_b16 v[232:233], v162 offset:0x1600
	ds_read_b64_tr_b16 v[234:235], v162 offset:0x1e00
	ds_read_b64_tr_b16 v[236:237], v162 offset:0x2600
	ds_read_b64_tr_b16 v[238:239], v162 offset:0x2e00
	ds_read_b64_tr_b16 v[248:249], v162 offset:0x3600
	ds_read_b64_tr_b16 v[250:251], v162 offset:0x3e00
	s_cbranch_scc1 .LBB0_931
	v_add_u32_e32 v163, 64, v159
	v_cmp_gt_i32_e64 s[70:71], 22, v163
	v_cmp_gt_i32_e64 s[72:73], 23, v163
	v_cmp_gt_i32_e64 s[68:69], 21, v163
	s_and_b64 s[70:71], s[72:73], s[70:71]
	v_cmp_gt_i32_e64 s[66:67], 20, v163
	s_and_b64 s[68:69], s[70:71], s[68:69]
	v_cmp_gt_i32_e64 s[64:65], 19, v163
	s_and_b64 s[66:67], s[68:69], s[66:67]
	v_cmp_gt_i32_e64 s[62:63], 18, v163
	s_and_b64 s[64:65], s[66:67], s[64:65]
	v_cmp_gt_i32_e64 s[60:61], 17, v163
	s_and_b64 s[62:63], s[64:65], s[62:63]
	v_cmp_gt_i32_e64 s[58:59], 16, v163
	s_and_b64 s[60:61], s[62:63], s[60:61]
	v_cmp_gt_i32_e64 s[56:57], 7, v163
	s_and_b64 s[58:59], s[60:61], s[58:59]
	v_cmp_gt_i32_e64 s[54:55], 6, v163
	s_and_b64 s[56:57], s[58:59], s[56:57]
	v_cmp_gt_i32_e64 s[52:53], 5, v163
	s_and_b64 s[54:55], s[56:57], s[54:55]
	v_cmp_gt_i32_e64 s[50:51], 4, v163
	s_and_b64 s[52:53], s[54:55], s[52:53]
	v_cmp_gt_i32_e64 s[48:49], 3, v163
	s_and_b64 s[50:51], s[52:53], s[50:51]
	v_cmp_gt_i32_e64 s[46:47], 2, v163
	s_and_b64 s[48:49], s[50:51], s[48:49]
	v_cmp_gt_i32_e64 s[44:45], 1, v163
	s_and_b64 s[46:47], s[48:49], s[46:47]
	v_cmp_gt_i32_e64 s[42:43], 0, v163
	s_and_b64 s[44:45], s[46:47], s[44:45]
	s_and_b64 s[42:43], s[44:45], s[42:43]
	v_cmp_gt_i32_e64 s[40:41], 54, v163
	v_cndmask_b32_e64 v84, v84, v204, s[42:43]
	v_cmp_gt_i32_e64 s[42:43], 55, v163
	v_cmp_gt_i32_e64 s[38:39], 53, v163
	s_and_b64 s[40:41], s[42:43], s[40:41]
	v_cmp_gt_i32_e64 s[36:37], 52, v163
	s_and_b64 s[38:39], s[40:41], s[38:39]
	v_cmp_gt_i32_e64 s[34:35], 51, v163
	s_and_b64 s[36:37], s[38:39], s[36:37]
	v_cmp_gt_i32_e64 s[30:31], 50, v163
	s_and_b64 s[34:35], s[36:37], s[34:35]
	v_cmp_gt_i32_e64 s[28:29], 49, v163
	s_and_b64 s[30:31], s[34:35], s[30:31]
	v_cmp_gt_i32_e64 s[26:27], 48, v163
	s_and_b64 s[28:29], s[30:31], s[28:29]
	v_cmp_gt_i32_e64 s[24:25], 39, v163
	s_and_b64 s[26:27], s[28:29], s[26:27]
	v_cmp_gt_i32_e64 s[22:23], 38, v163
	s_and_b64 s[24:25], s[26:27], s[24:25]
	v_cmp_gt_i32_e64 s[20:21], 37, v163
	s_and_b64 s[22:23], s[24:25], s[22:23]
	v_cmp_gt_i32_e64 s[18:19], 36, v163
	s_and_b64 s[20:21], s[22:23], s[20:21]
	v_cmp_gt_i32_e64 s[16:17], 35, v163
	s_and_b64 s[18:19], s[20:21], s[18:19]
	v_cmp_gt_i32_e64 s[14:15], 34, v163
	s_and_b64 s[16:17], s[18:19], s[16:17]
	v_cmp_gt_i32_e64 s[12:13], 33, v163
	s_and_b64 s[14:15], s[16:17], s[14:15]
	v_cmp_gt_i32_e32 vcc, 32, v163
	s_and_b64 s[12:13], s[14:15], s[12:13]
	s_and_b64 vcc, s[12:13], vcc
	v_cndmask_b32_e64 v99, v99, v204, s[72:73]
	v_cndmask_b32_e64 v98, v98, v204, s[70:71]
	v_cndmask_b32_e64 v97, v97, v204, s[68:69]
	v_cndmask_b32_e64 v96, v96, v204, s[66:67]
	v_cndmask_b32_e64 v95, v95, v204, s[64:65]
	v_cndmask_b32_e64 v94, v94, v204, s[62:63]
	v_cndmask_b32_e64 v93, v93, v204, s[60:61]
	v_cndmask_b32_e64 v92, v92, v204, s[58:59]
	v_cndmask_b32_e64 v91, v91, v204, s[56:57]
	v_cndmask_b32_e64 v90, v90, v204, s[54:55]
	v_cndmask_b32_e64 v89, v89, v204, s[52:53]
	v_cndmask_b32_e64 v88, v88, v204, s[50:51]
	v_cndmask_b32_e64 v87, v87, v204, s[48:49]
	v_cndmask_b32_e64 v86, v86, v204, s[46:47]
	v_cndmask_b32_e64 v85, v85, v204, s[44:45]
	v_cndmask_b32_e64 v83, v83, v204, s[42:43]
	v_cndmask_b32_e64 v82, v82, v204, s[40:41]
	v_cndmask_b32_e64 v81, v81, v204, s[38:39]
	v_cndmask_b32_e64 v80, v80, v204, s[36:37]
	v_cndmask_b32_e64 v79, v79, v204, s[34:35]
	v_cndmask_b32_e64 v78, v78, v204, s[30:31]
	v_cndmask_b32_e64 v77, v77, v204, s[28:29]
	v_cndmask_b32_e64 v76, v76, v204, s[26:27]
	v_cndmask_b32_e64 v75, v75, v204, s[24:25]
	v_cndmask_b32_e64 v74, v74, v204, s[22:23]
	v_cndmask_b32_e64 v73, v73, v204, s[20:21]
	v_cndmask_b32_e64 v72, v72, v204, s[18:19]
	v_cndmask_b32_e64 v71, v71, v204, s[16:17]
	v_cndmask_b32_e64 v70, v70, v204, s[14:15]
	v_cndmask_b32_e64 v69, v69, v204, s[12:13]
	v_cndmask_b32_e32 v68, v68, v204, vcc

.Lfa_b_2:
	v_mov_b32_e32 v243, v83
	v_exp_f32_e32 v164, v84
	v_exp_f32_e32 v85, v85
	v_exp_f32_e32 v86, v86
	v_exp_f32_e32 v87, v87
	v_exp_f32_e32 v88, v88
	v_exp_f32_e32 v89, v89
	v_exp_f32_e32 v90, v90
	v_exp_f32_e32 v165, v91
	v_add_f32_e32 v83, 0, v164
	v_add_f32_e32 v83, v85, v83
	v_add_f32_e32 v83, v86, v83
	v_add_f32_e32 v83, v87, v83
	v_cvt_pk_bf16_f32 v166, v164, v85
	v_cvt_pk_bf16_f32 v167, v86, v87
	v_cvt_pk_bf16_f32 v168, v88, v89
	v_cvt_pk_bf16_f32 v169, v90, v165
	v_exp_f32_e32 v91, v92
	v_exp_f32_e32 v92, v93
	s_waitcnt lgkmcnt(0)
	v_mfma_f32_32x32x16_bf16 v[52:67], v[166:169], v[144:147], v[52:67]
	v_mfma_f32_32x32x16_bf16 v[36:51], v[166:169], v[128:131], v[36:51]
	v_mfma_f32_32x32x16_bf16 v[20:35], v[166:169], v[206:209], v[20:35]
	v_mfma_f32_32x32x16_bf16 v[4:19], v[166:169], v[228:231], v[4:19]
	v_exp_f32_e32 v93, v94
	v_exp_f32_e32 v94, v95
	v_exp_f32_e32 v95, v96
	v_exp_f32_e32 v96, v97
	v_exp_f32_e32 v97, v98
	v_exp_f32_e32 v98, v99
	v_add_f32_e32 v83, v88, v83
	v_add_f32_e32 v83, v89, v83
	v_add_f32_e32 v83, v90, v83
	v_add_f32_e32 v83, v165, v83
	v_add_f32_e32 v83, v91, v83
	v_add_f32_e32 v83, v92, v83
	v_add_f32_e32 v83, v93, v83
	v_add_f32_e32 v83, v94, v83
	v_cvt_pk_bf16_f32 v86, v91, v92
	v_cvt_pk_bf16_f32 v87, v93, v94
	v_cvt_pk_bf16_f32 v88, v95, v96
	v_cvt_pk_bf16_f32 v89, v97, v98
	v_exp_f32_e32 v68, v68
	v_exp_f32_e32 v69, v69
	v_mfma_f32_32x32x16_bf16 v[52:67], v[86:89], v[140:143], v[52:67]
	v_mfma_f32_32x32x16_bf16 v[36:51], v[86:89], v[124:127], v[36:51]
	v_mfma_f32_32x32x16_bf16 v[20:35], v[86:89], v[212:215], v[20:35]
	v_mfma_f32_32x32x16_bf16 v[4:19], v[86:89], v[232:235], v[4:19]
	v_exp_f32_e32 v70, v70
	v_exp_f32_e32 v71, v71
	v_exp_f32_e32 v72, v72
	v_exp_f32_e32 v73, v73
	v_exp_f32_e32 v74, v74
	v_exp_f32_e32 v84, v75
	v_add_f32_e32 v83, v95, v83
	v_add_f32_e32 v83, v96, v83
	v_add_f32_e32 v83, v97, v83
	v_add_f32_e32 v83, v98, v83
	v_add_f32_e32 v83, v68, v83
	v_add_f32_e32 v83, v69, v83
	v_add_f32_e32 v83, v70, v83
	v_add_f32_e32 v83, v71, v83
	v_cvt_pk_bf16_f32 v68, v68, v69
	v_cvt_pk_bf16_f32 v69, v70, v71
	v_cvt_pk_bf16_f32 v70, v72, v73
	v_cvt_pk_bf16_f32 v71, v74, v84
	v_exp_f32_e32 v75, v76
	v_exp_f32_e32 v76, v77
	v_mfma_f32_32x32x16_bf16 v[52:67], v[68:71], v[136:139], v[52:67]
	v_mfma_f32_32x32x16_bf16 v[36:51], v[68:71], v[120:123], v[36:51]
	v_mfma_f32_32x32x16_bf16 v[20:35], v[68:71], v[220:223], v[20:35]
	v_mfma_f32_32x32x16_bf16 v[4:19], v[68:71], v[236:239], v[4:19]
	v_exp_f32_e32 v77, v78
	v_exp_f32_e32 v78, v79
	v_exp_f32_e32 v79, v80
	v_exp_f32_e32 v80, v81
	v_exp_f32_e32 v81, v82
	v_exp_f32_e32 v82, v243
	v_add_f32_e32 v83, v72, v83
	v_add_f32_e32 v83, v73, v83
	v_add_f32_e32 v83, v74, v83
	v_add_f32_e32 v83, v84, v83
	v_add_f32_e32 v83, v75, v83
	v_add_f32_e32 v83, v76, v83
	v_add_f32_e32 v83, v77, v83
	v_add_f32_e32 v83, v78, v83
	v_add_f32_e32 v83, v79, v83
	v_add_f32_e32 v83, v80, v83
	v_add_f32_e32 v83, v81, v83
	v_add_f32_e32 v83, v82, v83
	v_cvt_pk_bf16_f32 v72, v75, v76
	v_cvt_pk_bf16_f32 v73, v77, v78
	v_cvt_pk_bf16_f32 v74, v79, v80
	v_cvt_pk_bf16_f32 v75, v81, v82
	v_mov_b32_e32 v99, v83
	s_nop 1
	v_permlane32_swap_b32_e32 v83, v99
	v_mfma_f32_32x32x16_bf16 v[52:67], v[72:75], v[132:135], v[52:67]
	v_mfma_f32_32x32x16_bf16 v[36:51], v[72:75], v[116:119], v[36:51]
	v_mfma_f32_32x32x16_bf16 v[20:35], v[72:75], v[224:227], v[20:35]
	v_mfma_f32_32x32x16_bf16 v[4:19], v[72:75], v[248:251], v[4:19]
	v_add_f32_e32 v99, v83, v99
	v_fmac_f32_e32 v99, v161, v163
	v_mov_b32_e32 v161, v99
	s_branch .LBB0_916

.LBB0_937:
	s_and_saveexec_b64 s[2:3], s[10:11]
	ds_write_b32 v154, v161
	s_or_b64 exec, exec, s[2:3]
	s_waitcnt lgkmcnt(0)
	v_add_u32_e32 v2, s95, v2
	ds_read_b128 v[68:71], v2
	ds_read_b128 v[72:75], v2 offset:32
	v_readlane_b32 s2, v245, 62
	v_readlane_b32 s3, v245, 63
	s_mov_b32 s90, 0x1fffff0
	s_waitcnt lgkmcnt(1)
	v_rcp_f32_e32 v68, v68
	v_rcp_f32_e32 v69, v69
	v_rcp_f32_e32 v70, v70
	v_rcp_f32_e32 v71, v71
	s_waitcnt lgkmcnt(0)
	v_rcp_f32_e32 v72, v72
	v_pk_mul_f32 v[52:53], v[68:69], v[52:53]
	v_pk_mul_f32 v[36:37], v[68:69], v[36:37]
	v_pk_mul_f32 v[20:21], v[68:69], v[20:21]
	v_pk_mul_f32 v[4:5], v[68:69], v[4:5]
	v_pk_mul_f32 v[54:55], v[70:71], v[54:55]
	v_rcp_f32_e32 v73, v73
	v_pk_mul_f32 v[38:39], v[70:71], v[38:39]
	v_pk_mul_f32 v[22:23], v[70:71], v[22:23]
	v_pk_mul_f32 v[6:7], v[70:71], v[6:7]
	ds_read_b128 v[68:71], v2 offset:64
	v_pk_mul_f32 v[56:57], v[72:73], v[56:57]
	v_pk_mul_f32 v[40:41], v[72:73], v[40:41]
	v_rcp_f32_e32 v76, v74
	v_rcp_f32_e32 v77, v75
	v_pk_mul_f32 v[24:25], v[72:73], v[24:25]
	v_pk_mul_f32 v[8:9], v[72:73], v[8:9]
	ds_read_b128 v[72:75], v2 offset:96
	s_waitcnt lgkmcnt(1)
	v_rcp_f32_e32 v68, v68
	v_rcp_f32_e32 v69, v69
	v_rcp_f32_e32 v70, v70
	v_rcp_f32_e32 v71, v71
	v_mov_b32_e32 v2, v0
	v_pk_mul_f32 v[60:61], v[68:69], v[60:61]
	v_pk_mul_f32 v[44:45], v[68:69], v[44:45]
	v_pk_mul_f32 v[28:29], v[68:69], v[28:29]
	v_pk_mul_f32 v[12:13], v[68:69], v[12:13]
	s_waitcnt lgkmcnt(0)
	v_rcp_f32_e32 v68, v72
	v_rcp_f32_e32 v69, v73
	v_pk_mul_f32 v[62:63], v[70:71], v[62:63]
	v_pk_mul_f32 v[46:47], v[70:71], v[46:47]
	v_pk_mul_f32 v[30:31], v[70:71], v[30:31]
	v_pk_mul_f32 v[14:15], v[70:71], v[14:15]
	v_rcp_f32_e32 v70, v74
	v_rcp_f32_e32 v71, v75
	v_pk_mul_f32 v[64:65], v[68:69], v[64:65]
	v_pk_mul_f32 v[48:49], v[68:69], v[48:49]
	v_pk_mul_f32 v[32:33], v[68:69], v[32:33]
	v_pk_mul_f32 v[16:17], v[68:69], v[16:17]
	s_waitcnt lgkmcnt(0)
	v_pk_mul_f32 v[58:59], v[76:77], v[58:59]
	v_lshlrev_b32_e32 v68, 6, v2
	v_ashrrev_i32_e32 v69, 31, v68
	v_lshl_add_u64 v[148:149], v[68:69], 2, s[2:3]
	v_pk_mul_f32 v[42:43], v[76:77], v[42:43]
	v_pk_mul_f32 v[26:27], v[76:77], v[26:27]
	v_pk_mul_f32 v[10:11], v[76:77], v[10:11]
	v_pk_mul_f32 v[66:67], v[70:71], v[66:67]
	v_pk_mul_f32 v[50:51], v[70:71], v[50:51]
	v_pk_mul_f32 v[34:35], v[70:71], v[34:35]
	v_pk_mul_f32 v[18:19], v[70:71], v[18:19]
	global_store_dwordx4 v[148:149], v[52:55], off
	global_store_dwordx4 v[148:149], v[56:59], off offset:16
	global_store_dwordx4 v[148:149], v[60:63], off offset:32
	global_store_dwordx4 v[148:149], v[64:67], off offset:48
	global_store_dwordx4 v[148:149], v[36:39], off offset:64
	global_store_dwordx4 v[148:149], v[40:43], off offset:80
	global_store_dwordx4 v[148:149], v[44:47], off offset:96
	global_store_dwordx4 v[148:149], v[48:51], off offset:112
	global_store_dwordx4 v[148:149], v[20:23], off offset:128
	global_store_dwordx4 v[148:149], v[24:27], off offset:144
	global_store_dwordx4 v[148:149], v[28:31], off offset:160
	global_store_dwordx4 v[148:149], v[32:35], off offset:176
	global_store_dwordx4 v[148:149], v[4:7], off offset:192
	global_store_dwordx4 v[148:149], v[8:11], off offset:208
	global_store_dwordx4 v[148:149], v[12:15], off offset:224
	global_store_dwordx4 v[148:149], v[16:19], off offset:240
	v_mov_b32_e32 v163, 0
	v_mov_b32_e32 v12, v0
	v_mov_b32_e32 v18, v3
	v_readfirstlane_b32 s1, v12
	s_ashr_i32 s2, s1, 6
	v_and_b32_e32 v13, 31, v12
	s_lshl_b32 s3, s2, 5
	v_or_b32_e32 v4, s3, v13
	v_ashrrev_i32_e32 v5, 31, v4
	v_bfe_u32 v14, v12, 5, 1
	v_lshlrev_b64 v[4:5], 8, v[4:5]
	v_lshl_add_u64 v[4:5], s[6:7], 0, v[4:5]
	v_lshlrev_b32_e32 v2, 4, v14
	v_lshl_add_u64 v[4:5], v[4:5], 0, v[2:3]
	global_load_dwordx4 v[100:103], v[4:5], off
	global_load_dwordx4 v[104:107], v[4:5], off offset:32
	global_load_dwordx4 v[108:111], v[4:5], off offset:64
	global_load_dwordx4 v[112:115], v[4:5], off offset:96
	v_ashrrev_i32_e32 v5, 4, v12
	v_lshlrev_b32_e32 v6, 1, v5
	v_lshrrev_b32_e32 v7, 1, v5
	v_and_b32_e32 v4, 0x1fffff3, v5
	v_and_b32_e32 v6, 8, v6
	v_and_b32_e32 v7, 4, v7
	v_or3_b32 v4, v4, v6, v7
	v_and_b32_e32 v6, 15, v12
	v_bitop3_b32 v6, v5, v6, 7 bitop3:0x6c
	v_lshlrev_b32_e32 v6, 3, v6
	v_lshl_or_b32 v4, v4, 7, v6
	v_bfe_u32 v6, v12, 2, 2
	v_and_or_b32 v5, v5, s90, v6
	v_lshrrev_b32_e32 v6, 1, v12
	v_and_b32_e32 v6, 8, v6
	v_or3_b32 v5, v5, v6, v7
	v_lshlrev_b32_e32 v15, 3, v12
	v_lshlrev_b32_e32 v5, 7, v5
	v_and_b32_e32 v6, 0x60, v12
	v_and_b32_e32 v7, 24, v15
	v_or3_b32 v6, v5, v6, v7
	s_lshl_b32 s2, s2, 10
	v_ashrrev_i32_e32 v5, 31, v4
	v_lshlrev_b64 v[4:5], 1, v[4:5]
	s_add_i32 s8, s2, 0
	v_lshl_add_u64 v[8:9], s[80:81], 0, v[4:5]
	v_ashrrev_i32_e32 v7, 31, v6
	s_add_i32 m0, s8, 0x1c000
	v_lshlrev_b64 v[6:7], 1, v[6:7]
	global_load_lds_dwordx4 v[8:9], off
	v_lshl_add_u64 v[8:9], v[8:9], 0, s[84:85]
	s_add_i32 m0, s8, 0x1e000
	v_lshl_add_u64 v[10:11], s[96:97], 0, v[6:7]
	global_load_lds_dwordx4 v[8:9], off
	s_add_i32 m0, s8, 0xc000
	v_lshl_add_u64 v[8:9], v[10:11], 0, s[84:85]
	global_load_lds_dwordx4 v[10:11], off
	s_add_i32 m0, s8, 0xe000
	v_lshl_add_u64 v[10:11], s[88:89], 0, v[6:7]
	global_load_lds_dwordx4 v[8:9], off
	v_lshl_add_u64 v[8:9], s[82:83], 0, v[4:5]
	s_add_i32 m0, s8, 0x18000
	s_and_b32 s1, s1, 0x3fffffc0
	global_load_lds_dwordx4 v[8:9], off
	v_lshl_add_u64 v[8:9], v[8:9], 0, s[84:85]
	s_add_i32 m0, s8, 0x1a000
	v_lshl_add_u64 v[150:151], s[74:75], 0, v[4:5]
	global_load_lds_dwordx4 v[8:9], off
	s_add_i32 m0, s8, 0x8000
	v_lshl_add_u64 v[8:9], v[10:11], 0, s[84:85]
	global_load_lds_dwordx4 v[10:11], off
	s_add_i32 m0, s8, 0xa000
	v_lshlrev_b32_e32 v4, 1, v12
	global_load_lds_dwordx4 v[8:9], off
	s_lshl_b32 s1, s1, 2
	v_and_b32_e32 v4, 32, v4
	v_lshlrev_b32_e32 v5, 4, v12
	s_add_i32 s78, s1, 0
	s_add_i32 s79, s3, s9
	v_lshl_add_u64 v[152:153], s[76:77], 0, v[6:7]
	v_and_b32_e32 v6, 0xc0, v5
	v_and_or_b32 v4, v15, s93, v4
	s_movk_i32 s2, 0x70
	s_addk_i32 s3, 0xff40
	s_add_i32 s78, s78, 0x20400
	v_and_b32_e32 v8, 63, v12
	v_lshlrev_b32_e32 v9, 3, v14
	s_waitcnt vmcnt(0)
	v_and_b32_e32 v7, 0x70, v5
	v_bitop3_b32 v156, v2, v5, s2 bitop3:0x78
	s_movk_i32 s2, 0x60
	v_add3_u32 v160, v6, 0, v4
	v_or_b32_e32 v4, s3, v13
	v_mov_b32_e32 v19, v3
	v_lshlrev_b32_e32 v154, 8, v13
	v_bitop3_b32 v157, v2, v7, 32 bitop3:0x36
	v_bitop3_b32 v158, v2, v7, 64 bitop3:0x36
	v_bitop3_b32 v159, v2, v7, s2 bitop3:0x36
	v_cmp_gt_u32_e64 s[10:11], 32, v8
	v_lshl_add_u32 v155, v13, 2, s78
	v_sub_u32_e32 v161, v4, v9
	v_mov_b32_e32 v4, v3
	v_mov_b32_e32 v5, v3
	v_mov_b32_e32 v6, v3
	v_mov_b32_e32 v7, v3
	v_mov_b32_e32 v8, v3
	v_mov_b32_e32 v9, v3
	v_mov_b32_e32 v10, v3
	v_mov_b32_e32 v11, v3
	v_mov_b32_e32 v12, v3
	v_mov_b32_e32 v13, v3
	v_mov_b32_e32 v14, v3
	v_mov_b32_e32 v15, v3
	v_mov_b32_e32 v16, v3
	v_mov_b32_e32 v17, v3
	v_mov_b64_e32 v[34:35], v[18:19]
	v_mov_b64_e32 v[50:51], v[18:19]
	v_mov_b64_e32 v[66:67], v[18:19]
	s_add_i32 s1, s8, 0x10000
	s_or_b32 s80, s79, 31
	v_mov_b32_e32 v162, 0xf149f2ca
	v_mov_b32_e32 v240, 0xf149f2ca
	v_mov_b64_e32 v[184:185], 0
	v_mov_b64_e32 v[186:187], 0
	v_mov_b64_e32 v[188:189], 0
	v_mov_b64_e32 v[190:191], 0
	v_mov_b64_e32 v[192:193], 0
	v_mov_b64_e32 v[194:195], 0
	v_mov_b64_e32 v[196:197], 0
	v_mov_b64_e32 v[198:199], 0
	s_mov_b32 s2, s9
	v_mov_b64_e32 v[32:33], v[16:17]
	v_mov_b64_e32 v[30:31], v[14:15]
	v_mov_b64_e32 v[28:29], v[12:13]
	v_mov_b64_e32 v[26:27], v[10:11]
	v_mov_b64_e32 v[24:25], v[8:9]
	v_mov_b64_e32 v[22:23], v[6:7]
	v_mov_b64_e32 v[20:21], v[4:5]
	v_mov_b64_e32 v[48:49], v[16:17]
	v_mov_b64_e32 v[46:47], v[14:15]
	v_mov_b64_e32 v[44:45], v[12:13]
	v_mov_b64_e32 v[42:43], v[10:11]
	v_mov_b64_e32 v[40:41], v[8:9]
	v_mov_b64_e32 v[38:39], v[6:7]
	v_mov_b64_e32 v[36:37], v[4:5]
	v_mov_b64_e32 v[64:65], v[16:17]
	v_mov_b64_e32 v[62:63], v[14:15]
	v_mov_b64_e32 v[60:61], v[12:13]
	v_mov_b64_e32 v[58:59], v[10:11]
	v_mov_b64_e32 v[56:57], v[8:9]
	v_mov_b64_e32 v[54:55], v[6:7]
	v_mov_b64_e32 v[52:53], v[4:5]
	s_waitcnt vmcnt(0) lgkmcnt(0)
	s_barrier
	s_branch .LBB0_943
.LBB0_942:
	s_waitcnt vmcnt(0)
	s_add_i32 s92, s92, -2
	s_addk_i32 s0, 0x8000
	s_addk_i32 s2, 0xff80
	v_add_u32_e32 v161, 0x80, v161
	s_and_b64 vcc, exec, s[6:7]
	s_waitcnt vmcnt(0) lgkmcnt(0)
	s_barrier
	s_cbranch_vccnz .LBB0_963

.LBB0_947:
	s_add_i32 s4, s0, 0xc000
	s_and_b32 s4, s4, 0xc000
	s_add_i32 s12, s4, 0
	s_add_i32 s12, s12, 0x10000
	v_add_u32_e32 v76, s12, v154
	v_add_u32_e32 v77, v76, v156
	ds_read_b128 v[68:71], v77 offset:0
	ds_read_b128 v[72:75], v77 offset:0x2000
	v_add_u32_e32 v77, v76, v157
	ds_read_b128 v[116:119], v77 offset:0
	ds_read_b128 v[120:123], v77 offset:0x2000
	v_add_u32_e32 v77, v76, v158
	ds_read_b128 v[124:127], v77 offset:0
	ds_read_b128 v[128:131], v77 offset:0x2000
	v_add_u32_e32 v76, v76, v159
	ds_read_b128 v[132:135], v76 offset:0
	ds_read_b128 v[136:139], v76 offset:0x2000
	s_waitcnt lgkmcnt(4)
	s_add_i32 s3, s2, 0xff
	s_cmp_le_u32 s3, s79
	v_mfma_f32_32x32x16_bf16 v[84:99], v[68:71], v[100:103], v[184:199]
	v_mfma_f32_32x32x16_bf16 v[84:99], v[116:119], v[104:107], v[84:99]
	v_mfma_f32_32x32x16_bf16 v[68:83], v[72:75], v[100:103], v[184:199]
	v_mfma_f32_32x32x16_bf16 v[68:83], v[120:123], v[104:107], v[68:83]
	s_waitcnt lgkmcnt(0)
	v_mfma_f32_32x32x16_bf16 v[84:99], v[124:127], v[108:111], v[84:99]
	v_mfma_f32_32x32x16_bf16 v[84:99], v[132:135], v[112:115], v[84:99]
	v_mfma_f32_32x32x16_bf16 v[68:83], v[128:131], v[108:111], v[68:83]
	v_mfma_f32_32x32x16_bf16 v[68:83], v[136:139], v[112:115], v[68:83]
	v_add_u32_e32 v164, s4, v160
	ds_read_b64_tr_b16 v[144:145], v164 offset:0
	ds_read_b64_tr_b16 v[146:147], v164 offset:0x800
	ds_read_b64_tr_b16 v[140:141], v164 offset:0x1000
	ds_read_b64_tr_b16 v[142:143], v164 offset:0x1800
	ds_read_b64_tr_b16 v[136:137], v164 offset:0x2000
	ds_read_b64_tr_b16 v[138:139], v164 offset:0x2800
	ds_read_b64_tr_b16 v[132:133], v164 offset:0x3000
	ds_read_b64_tr_b16 v[134:135], v164 offset:0x3800
	ds_read_b64_tr_b16 v[128:129], v164 offset:0x200
	ds_read_b64_tr_b16 v[130:131], v164 offset:0xa00
	ds_read_b64_tr_b16 v[124:125], v164 offset:0x1200
	ds_read_b64_tr_b16 v[126:127], v164 offset:0x1a00
	ds_read_b64_tr_b16 v[120:121], v164 offset:0x2200
	ds_read_b64_tr_b16 v[122:123], v164 offset:0x2a00
	ds_read_b64_tr_b16 v[116:117], v164 offset:0x3200
	ds_read_b64_tr_b16 v[118:119], v164 offset:0x3a00
	ds_read_b64_tr_b16 v[206:207], v164 offset:0x400
	ds_read_b64_tr_b16 v[208:209], v164 offset:0xc00
	ds_read_b64_tr_b16 v[212:213], v164 offset:0x1400
	ds_read_b64_tr_b16 v[214:215], v164 offset:0x1c00
	ds_read_b64_tr_b16 v[220:221], v164 offset:0x2400
	ds_read_b64_tr_b16 v[222:223], v164 offset:0x2c00
	ds_read_b64_tr_b16 v[224:225], v164 offset:0x3400
	ds_read_b64_tr_b16 v[226:227], v164 offset:0x3c00
	ds_read_b64_tr_b16 v[228:229], v164 offset:0x600
	ds_read_b64_tr_b16 v[230:231], v164 offset:0xe00
	ds_read_b64_tr_b16 v[232:233], v164 offset:0x1600
	ds_read_b64_tr_b16 v[234:235], v164 offset:0x1e00
	ds_read_b64_tr_b16 v[236:237], v164 offset:0x2600
	ds_read_b64_tr_b16 v[238:239], v164 offset:0x2e00
	ds_read_b64_tr_b16 v[248:249], v164 offset:0x3600
	ds_read_b64_tr_b16 v[250:251], v164 offset:0x3e00
	s_cbranch_scc1 .LBB0_949
	v_cmp_gt_i32_e64 s[70:71], 22, v161
	v_cmp_gt_i32_e64 s[72:73], 23, v161
	v_cmp_gt_i32_e64 s[68:69], 21, v161
	s_and_b64 s[70:71], s[72:73], s[70:71]
	v_cmp_gt_i32_e64 s[66:67], 20, v161
	s_and_b64 s[68:69], s[70:71], s[68:69]
	v_cmp_gt_i32_e64 s[64:65], 19, v161
	s_and_b64 s[66:67], s[68:69], s[66:67]
	v_cmp_gt_i32_e64 s[62:63], 18, v161
	s_and_b64 s[64:65], s[66:67], s[64:65]
	v_cmp_gt_i32_e64 s[60:61], 17, v161
	s_and_b64 s[62:63], s[64:65], s[62:63]
	v_cmp_gt_i32_e64 s[58:59], 16, v161
	s_and_b64 s[60:61], s[62:63], s[60:61]
	v_cmp_gt_i32_e64 s[56:57], 7, v161
	s_and_b64 s[58:59], s[60:61], s[58:59]
	v_cmp_gt_i32_e64 s[54:55], 6, v161
	s_and_b64 s[56:57], s[58:59], s[56:57]
	v_cmp_gt_i32_e64 s[52:53], 5, v161
	s_and_b64 s[54:55], s[56:57], s[54:55]
	v_cmp_gt_i32_e64 s[50:51], 4, v161
	s_and_b64 s[52:53], s[54:55], s[52:53]
	v_cmp_gt_i32_e64 s[48:49], 3, v161
	s_and_b64 s[50:51], s[52:53], s[50:51]
	v_cmp_gt_i32_e64 s[46:47], 2, v161
	s_and_b64 s[48:49], s[50:51], s[48:49]
	v_cmp_gt_i32_e64 s[44:45], 1, v161
	s_and_b64 s[46:47], s[48:49], s[46:47]
	v_cmp_gt_i32_e64 s[42:43], 0, v161
	s_and_b64 s[44:45], s[46:47], s[44:45]
	s_and_b64 s[42:43], s[44:45], s[42:43]
	v_cmp_gt_i32_e64 s[40:41], 54, v161
	v_cndmask_b32_e64 v84, v84, v204, s[42:43]
	v_cmp_gt_i32_e64 s[42:43], 55, v161
	v_cmp_gt_i32_e64 s[38:39], 53, v161
	s_and_b64 s[40:41], s[42:43], s[40:41]
	v_cmp_gt_i32_e64 s[36:37], 52, v161
	s_and_b64 s[38:39], s[40:41], s[38:39]
	v_cmp_gt_i32_e64 s[34:35], 51, v161
	s_and_b64 s[36:37], s[38:39], s[36:37]
	v_cmp_gt_i32_e64 s[30:31], 50, v161
	s_and_b64 s[34:35], s[36:37], s[34:35]
	v_cmp_gt_i32_e64 s[28:29], 49, v161
	s_and_b64 s[30:31], s[34:35], s[30:31]
	v_cmp_gt_i32_e64 s[26:27], 48, v161
	s_and_b64 s[28:29], s[30:31], s[28:29]
	v_cmp_gt_i32_e64 s[24:25], 39, v161
	s_and_b64 s[26:27], s[28:29], s[26:27]
	v_cmp_gt_i32_e64 s[22:23], 38, v161
	s_and_b64 s[24:25], s[26:27], s[24:25]
	v_cmp_gt_i32_e64 s[20:21], 37, v161
	s_and_b64 s[22:23], s[24:25], s[22:23]
	v_cmp_gt_i32_e64 s[18:19], 36, v161
	s_and_b64 s[20:21], s[22:23], s[20:21]
	v_cmp_gt_i32_e64 s[16:17], 35, v161
	s_and_b64 s[18:19], s[20:21], s[18:19]
	v_cmp_gt_i32_e64 s[14:15], 34, v161
	s_and_b64 s[16:17], s[18:19], s[16:17]
	v_cmp_gt_i32_e64 s[12:13], 33, v161
	s_and_b64 s[14:15], s[16:17], s[14:15]
	v_cmp_gt_i32_e32 vcc, 32, v161
	s_and_b64 s[12:13], s[14:15], s[12:13]
	s_and_b64 vcc, s[12:13], vcc
	v_cndmask_b32_e64 v99, v99, v204, s[72:73]
	v_cndmask_b32_e64 v98, v98, v204, s[70:71]
	v_cndmask_b32_e64 v97, v97, v204, s[68:69]
	v_cndmask_b32_e64 v96, v96, v204, s[66:67]
	v_cndmask_b32_e64 v95, v95, v204, s[64:65]
	v_cndmask_b32_e64 v94, v94, v204, s[62:63]
	v_cndmask_b32_e64 v93, v93, v204, s[60:61]
	v_cndmask_b32_e64 v92, v92, v204, s[58:59]
	v_cndmask_b32_e64 v91, v91, v204, s[56:57]
	v_cndmask_b32_e64 v90, v90, v204, s[54:55]
	v_cndmask_b32_e64 v89, v89, v204, s[52:53]
	v_cndmask_b32_e64 v88, v88, v204, s[50:51]
	v_cndmask_b32_e64 v87, v87, v204, s[48:49]
	v_cndmask_b32_e64 v86, v86, v204, s[46:47]
	v_cndmask_b32_e64 v85, v85, v204, s[44:45]
	v_cndmask_b32_e64 v83, v83, v204, s[42:43]
	v_cndmask_b32_e64 v82, v82, v204, s[40:41]
	v_cndmask_b32_e64 v81, v81, v204, s[38:39]
	v_cndmask_b32_e64 v80, v80, v204, s[36:37]
	v_cndmask_b32_e64 v79, v79, v204, s[34:35]
	v_cndmask_b32_e64 v78, v78, v204, s[30:31]
	v_cndmask_b32_e64 v77, v77, v204, s[28:29]
	v_cndmask_b32_e64 v76, v76, v204, s[26:27]
	v_cndmask_b32_e64 v75, v75, v204, s[24:25]
	v_cndmask_b32_e64 v74, v74, v204, s[22:23]
	v_cndmask_b32_e64 v73, v73, v204, s[20:21]
	v_cndmask_b32_e64 v72, v72, v204, s[18:19]
	v_cndmask_b32_e64 v71, v71, v204, s[16:17]
	v_cndmask_b32_e64 v70, v70, v204, s[14:15]
	v_cndmask_b32_e64 v69, v69, v204, s[12:13]
	v_cndmask_b32_e32 v68, v68, v204, vcc

.LBB0_950:
	v_cmp_gt_f32_e32 vcc, 1.0, v165
	s_cbranch_vccz .Lfa_a_1
	s_and_saveexec_b64 s[12:13], s[10:11]
	ds_write_b32 v155, v165 offset:128
	s_or_b64 exec, exec, s[12:13]
	s_waitcnt lgkmcnt(0)
	v_add_u32_e32 v180, s78, v2
	ds_read_b128 v[168:171], v180 offset:224
	ds_read_b128 v[172:175], v180 offset:192
	ds_read_b128 v[176:179], v180 offset:160
	ds_read_b128 v[180:183], v180 offset:128
	s_waitcnt lgkmcnt(0)
	s_waitcnt lgkmcnt(0)
	v_pk_mul_f32 v[64:65], v[168:169], v[64:65]
	v_pk_mul_f32 v[60:61], v[172:173], v[60:61]
	v_pk_mul_f32 v[56:57], v[176:177], v[56:57]
	v_pk_mul_f32 v[66:67], v[170:171], v[66:67]
	v_pk_mul_f32 v[62:63], v[174:175], v[62:63]
	v_pk_mul_f32 v[58:59], v[178:179], v[58:59]
	v_pk_mul_f32 v[54:55], v[182:183], v[54:55]
	v_pk_mul_f32 v[52:53], v[180:181], v[52:53]
	v_pk_mul_f32 v[48:49], v[168:169], v[48:49]
	v_pk_mul_f32 v[44:45], v[172:173], v[44:45]
	v_pk_mul_f32 v[40:41], v[176:177], v[40:41]
	v_pk_mul_f32 v[50:51], v[170:171], v[50:51]
	v_pk_mul_f32 v[46:47], v[174:175], v[46:47]
	v_pk_mul_f32 v[42:43], v[178:179], v[42:43]
	v_pk_mul_f32 v[38:39], v[182:183], v[38:39]
	v_pk_mul_f32 v[36:37], v[180:181], v[36:37]
	v_pk_mul_f32 v[32:33], v[168:169], v[32:33]
	v_pk_mul_f32 v[28:29], v[172:173], v[28:29]
	v_pk_mul_f32 v[24:25], v[176:177], v[24:25]
	v_pk_mul_f32 v[34:35], v[170:171], v[34:35]
	v_pk_mul_f32 v[30:31], v[174:175], v[30:31]
	v_pk_mul_f32 v[26:27], v[178:179], v[26:27]
	v_pk_mul_f32 v[22:23], v[182:183], v[22:23]
	v_pk_mul_f32 v[20:21], v[180:181], v[20:21]
	v_pk_mul_f32 v[16:17], v[168:169], v[16:17]
	v_pk_mul_f32 v[12:13], v[172:173], v[12:13]
	v_pk_mul_f32 v[8:9], v[176:177], v[8:9]
	v_pk_mul_f32 v[18:19], v[170:171], v[18:19]
	v_pk_mul_f32 v[14:15], v[174:175], v[14:15]
	v_pk_mul_f32 v[10:11], v[178:179], v[10:11]
	v_pk_mul_f32 v[6:7], v[182:183], v[6:7]
	v_pk_mul_f32 v[4:5], v[180:181], v[4:5]
.Lfa_a_1:
	v_mov_b32_e32 v243, v83
	v_exp_f32_e32 v166, v84
	v_exp_f32_e32 v85, v85
	v_exp_f32_e32 v86, v86
	v_exp_f32_e32 v87, v87
	v_exp_f32_e32 v88, v88
	v_exp_f32_e32 v89, v89
	v_exp_f32_e32 v90, v90
	v_exp_f32_e32 v167, v91
	v_add_f32_e32 v83, 0, v166
	v_add_f32_e32 v83, v85, v83
	v_add_f32_e32 v83, v86, v83
	v_add_f32_e32 v83, v87, v83
	v_cvt_pk_bf16_f32 v168, v166, v85
	v_cvt_pk_bf16_f32 v169, v86, v87
	v_cvt_pk_bf16_f32 v170, v88, v89
	v_cvt_pk_bf16_f32 v171, v90, v167
	v_exp_f32_e32 v91, v92
	v_exp_f32_e32 v92, v93
	s_waitcnt lgkmcnt(0)
	v_mfma_f32_32x32x16_bf16 v[52:67], v[168:171], v[144:147], v[52:67]
	v_mfma_f32_32x32x16_bf16 v[36:51], v[168:171], v[128:131], v[36:51]
	v_mfma_f32_32x32x16_bf16 v[20:35], v[168:171], v[206:209], v[20:35]
	v_mfma_f32_32x32x16_bf16 v[4:19], v[168:171], v[228:231], v[4:19]
	v_exp_f32_e32 v93, v94
	v_exp_f32_e32 v94, v95
	v_exp_f32_e32 v95, v96
	v_exp_f32_e32 v96, v97
	v_exp_f32_e32 v97, v98
	v_exp_f32_e32 v98, v99
	v_add_f32_e32 v83, v88, v83
	v_add_f32_e32 v83, v89, v83
	v_add_f32_e32 v83, v90, v83
	v_add_f32_e32 v83, v167, v83
	v_add_f32_e32 v83, v91, v83
	v_add_f32_e32 v83, v92, v83
	v_add_f32_e32 v83, v93, v83
	v_add_f32_e32 v83, v94, v83
	v_cvt_pk_bf16_f32 v86, v91, v92
	v_cvt_pk_bf16_f32 v87, v93, v94
	v_cvt_pk_bf16_f32 v88, v95, v96
	v_cvt_pk_bf16_f32 v89, v97, v98
	v_exp_f32_e32 v68, v68
	v_exp_f32_e32 v69, v69
	v_mfma_f32_32x32x16_bf16 v[52:67], v[86:89], v[140:143], v[52:67]
	v_mfma_f32_32x32x16_bf16 v[36:51], v[86:89], v[124:127], v[36:51]
	v_mfma_f32_32x32x16_bf16 v[20:35], v[86:89], v[212:215], v[20:35]
	v_mfma_f32_32x32x16_bf16 v[4:19], v[86:89], v[232:235], v[4:19]
	v_exp_f32_e32 v70, v70
	v_exp_f32_e32 v71, v71
	v_exp_f32_e32 v72, v72
	v_exp_f32_e32 v73, v73
	v_exp_f32_e32 v74, v74
	v_exp_f32_e32 v84, v75
	v_add_f32_e32 v83, v95, v83
	v_add_f32_e32 v83, v96, v83
	v_add_f32_e32 v83, v97, v83
	v_add_f32_e32 v83, v98, v83
	v_add_f32_e32 v83, v68, v83
	v_add_f32_e32 v83, v69, v83
	v_add_f32_e32 v83, v70, v83
	v_add_f32_e32 v83, v71, v83
	v_cvt_pk_bf16_f32 v68, v68, v69
	v_cvt_pk_bf16_f32 v69, v70, v71
	v_cvt_pk_bf16_f32 v70, v72, v73
	v_cvt_pk_bf16_f32 v71, v74, v84
	v_exp_f32_e32 v75, v76
	v_exp_f32_e32 v76, v77
	v_mfma_f32_32x32x16_bf16 v[52:67], v[68:71], v[136:139], v[52:67]
	v_mfma_f32_32x32x16_bf16 v[36:51], v[68:71], v[120:123], v[36:51]
	v_mfma_f32_32x32x16_bf16 v[20:35], v[68:71], v[220:223], v[20:35]
	v_mfma_f32_32x32x16_bf16 v[4:19], v[68:71], v[236:239], v[4:19]
	v_exp_f32_e32 v77, v78
	v_exp_f32_e32 v78, v79
	v_exp_f32_e32 v79, v80
	v_exp_f32_e32 v80, v81
	v_exp_f32_e32 v81, v82
	v_exp_f32_e32 v82, v243
	v_add_f32_e32 v83, v72, v83
	v_add_f32_e32 v83, v73, v83
	v_add_f32_e32 v83, v74, v83
	v_add_f32_e32 v83, v84, v83
	v_add_f32_e32 v83, v75, v83
	v_add_f32_e32 v83, v76, v83
	v_add_f32_e32 v83, v77, v83
	v_add_f32_e32 v83, v78, v83
	v_add_f32_e32 v83, v79, v83
	v_add_f32_e32 v83, v80, v83
	v_add_f32_e32 v83, v81, v83
	v_add_f32_e32 v83, v82, v83
	v_cvt_pk_bf16_f32 v72, v75, v76
	v_cvt_pk_bf16_f32 v73, v77, v78
	v_cvt_pk_bf16_f32 v74, v79, v80
	v_cvt_pk_bf16_f32 v75, v81, v82
	v_mov_b32_e32 v99, v83
	s_nop 1
	v_permlane32_swap_b32_e32 v83, v99
	v_mfma_f32_32x32x16_bf16 v[52:67], v[72:75], v[132:135], v[52:67]
	v_mfma_f32_32x32x16_bf16 v[36:51], v[72:75], v[116:119], v[36:51]
	v_mfma_f32_32x32x16_bf16 v[20:35], v[72:75], v[224:227], v[20:35]
	v_mfma_f32_32x32x16_bf16 v[4:19], v[72:75], v[248:251], v[4:19]
	v_add_f32_e32 v99, v83, v99
	v_fmac_f32_e32 v99, v163, v165
	v_mov_b32_e32 v163, v99
	s_add_i32 s3, s2, 0x80
	s_cmp_gt_i32 s3, s80
	s_cbranch_scc1 .LBB0_942
.LBB0_955:
	s_add_i32 s4, s0, 0x8000
	s_and_b32 s4, s4, 0xc000
	s_add_i32 s12, s4, 0
	s_add_i32 s12, s12, 0x10000
	v_add_u32_e32 v76, s12, v154
	v_add_u32_e32 v77, v76, v156
	ds_read_b128 v[68:71], v77 offset:0
	ds_read_b128 v[72:75], v77 offset:0x2000
	v_add_u32_e32 v77, v76, v157
	ds_read_b128 v[116:119], v77 offset:0
	ds_read_b128 v[120:123], v77 offset:0x2000
	v_add_u32_e32 v77, v76, v158
	ds_read_b128 v[124:127], v77 offset:0
	ds_read_b128 v[128:131], v77 offset:0x2000
	v_add_u32_e32 v76, v76, v159
	ds_read_b128 v[132:135], v76 offset:0
	ds_read_b128 v[136:139], v76 offset:0x2000
	s_waitcnt lgkmcnt(4)
	s_add_i32 s3, s2, 0xbf
	s_cmp_le_i32 s3, s79
	v_mfma_f32_32x32x16_bf16 v[84:99], v[68:71], v[100:103], v[184:199]
	v_mfma_f32_32x32x16_bf16 v[84:99], v[116:119], v[104:107], v[84:99]
	v_mfma_f32_32x32x16_bf16 v[68:83], v[72:75], v[100:103], v[184:199]
	v_mfma_f32_32x32x16_bf16 v[68:83], v[120:123], v[104:107], v[68:83]
	s_waitcnt lgkmcnt(0)
	v_mfma_f32_32x32x16_bf16 v[84:99], v[124:127], v[108:111], v[84:99]
	v_mfma_f32_32x32x16_bf16 v[84:99], v[132:135], v[112:115], v[84:99]
	v_mfma_f32_32x32x16_bf16 v[68:83], v[128:131], v[108:111], v[68:83]
	v_mfma_f32_32x32x16_bf16 v[68:83], v[136:139], v[112:115], v[68:83]
	v_add_u32_e32 v164, s4, v160
	ds_read_b64_tr_b16 v[144:145], v164 offset:0
	ds_read_b64_tr_b16 v[146:147], v164 offset:0x800
	ds_read_b64_tr_b16 v[140:141], v164 offset:0x1000
	ds_read_b64_tr_b16 v[142:143], v164 offset:0x1800
	ds_read_b64_tr_b16 v[136:137], v164 offset:0x2000
	ds_read_b64_tr_b16 v[138:139], v164 offset:0x2800
	ds_read_b64_tr_b16 v[132:133], v164 offset:0x3000
	ds_read_b64_tr_b16 v[134:135], v164 offset:0x3800
	ds_read_b64_tr_b16 v[128:129], v164 offset:0x200
	ds_read_b64_tr_b16 v[130:131], v164 offset:0xa00
	ds_read_b64_tr_b16 v[124:125], v164 offset:0x1200
	ds_read_b64_tr_b16 v[126:127], v164 offset:0x1a00
	ds_read_b64_tr_b16 v[120:121], v164 offset:0x2200
	ds_read_b64_tr_b16 v[122:123], v164 offset:0x2a00
	ds_read_b64_tr_b16 v[116:117], v164 offset:0x3200
	ds_read_b64_tr_b16 v[118:119], v164 offset:0x3a00
	ds_read_b64_tr_b16 v[206:207], v164 offset:0x400
	ds_read_b64_tr_b16 v[208:209], v164 offset:0xc00
	ds_read_b64_tr_b16 v[212:213], v164 offset:0x1400
	ds_read_b64_tr_b16 v[214:215], v164 offset:0x1c00
	ds_read_b64_tr_b16 v[220:221], v164 offset:0x2400
	ds_read_b64_tr_b16 v[222:223], v164 offset:0x2c00
	ds_read_b64_tr_b16 v[224:225], v164 offset:0x3400
	ds_read_b64_tr_b16 v[226:227], v164 offset:0x3c00
	ds_read_b64_tr_b16 v[228:229], v164 offset:0x600
	ds_read_b64_tr_b16 v[230:231], v164 offset:0xe00
	ds_read_b64_tr_b16 v[232:233], v164 offset:0x1600
	ds_read_b64_tr_b16 v[234:235], v164 offset:0x1e00
	ds_read_b64_tr_b16 v[236:237], v164 offset:0x2600
	ds_read_b64_tr_b16 v[238:239], v164 offset:0x2e00
	ds_read_b64_tr_b16 v[248:249], v164 offset:0x3600
	ds_read_b64_tr_b16 v[250:251], v164 offset:0x3e00
	s_cbranch_scc1 .LBB0_957
	v_add_u32_e32 v165, 64, v161
	v_cmp_gt_i32_e64 s[70:71], 22, v165
	v_cmp_gt_i32_e64 s[72:73], 23, v165
	v_cmp_gt_i32_e64 s[68:69], 21, v165
	s_and_b64 s[70:71], s[72:73], s[70:71]
	v_cmp_gt_i32_e64 s[66:67], 20, v165
	s_and_b64 s[68:69], s[70:71], s[68:69]
	v_cmp_gt_i32_e64 s[64:65], 19, v165
	s_and_b64 s[66:67], s[68:69], s[66:67]
	v_cmp_gt_i32_e64 s[62:63], 18, v165
	s_and_b64 s[64:65], s[66:67], s[64:65]
	v_cmp_gt_i32_e64 s[60:61], 17, v165
	s_and_b64 s[62:63], s[64:65], s[62:63]
	v_cmp_gt_i32_e64 s[58:59], 16, v165
	s_and_b64 s[60:61], s[62:63], s[60:61]
	v_cmp_gt_i32_e64 s[56:57], 7, v165
	s_and_b64 s[58:59], s[60:61], s[58:59]
	v_cmp_gt_i32_e64 s[54:55], 6, v165
	s_and_b64 s[56:57], s[58:59], s[56:57]
	v_cmp_gt_i32_e64 s[52:53], 5, v165
	s_and_b64 s[54:55], s[56:57], s[54:55]
	v_cmp_gt_i32_e64 s[50:51], 4, v165
	s_and_b64 s[52:53], s[54:55], s[52:53]
	v_cmp_gt_i32_e64 s[48:49], 3, v165
	s_and_b64 s[50:51], s[52:53], s[50:51]
	v_cmp_gt_i32_e64 s[46:47], 2, v165
	s_and_b64 s[48:49], s[50:51], s[48:49]
	v_cmp_gt_i32_e64 s[44:45], 1, v165
	s_and_b64 s[46:47], s[48:49], s[46:47]
	v_cmp_gt_i32_e64 s[42:43], 0, v165
	s_and_b64 s[44:45], s[46:47], s[44:45]
	s_and_b64 s[42:43], s[44:45], s[42:43]
	v_cmp_gt_i32_e64 s[40:41], 54, v165
	v_cndmask_b32_e64 v84, v84, v204, s[42:43]
	v_cmp_gt_i32_e64 s[42:43], 55, v165
	v_cmp_gt_i32_e64 s[38:39], 53, v165
	s_and_b64 s[40:41], s[42:43], s[40:41]
	v_cmp_gt_i32_e64 s[36:37], 52, v165
	s_and_b64 s[38:39], s[40:41], s[38:39]
	v_cmp_gt_i32_e64 s[34:35], 51, v165
	s_and_b64 s[36:37], s[38:39], s[36:37]
	v_cmp_gt_i32_e64 s[30:31], 50, v165
	s_and_b64 s[34:35], s[36:37], s[34:35]
	v_cmp_gt_i32_e64 s[28:29], 49, v165
	s_and_b64 s[30:31], s[34:35], s[30:31]
	v_cmp_gt_i32_e64 s[26:27], 48, v165
	s_and_b64 s[28:29], s[30:31], s[28:29]
	v_cmp_gt_i32_e64 s[24:25], 39, v165
	s_and_b64 s[26:27], s[28:29], s[26:27]
	v_cmp_gt_i32_e64 s[22:23], 38, v165
	s_and_b64 s[24:25], s[26:27], s[24:25]
	v_cmp_gt_i32_e64 s[20:21], 37, v165
	s_and_b64 s[22:23], s[24:25], s[22:23]
	v_cmp_gt_i32_e64 s[18:19], 36, v165
	s_and_b64 s[20:21], s[22:23], s[20:21]
	v_cmp_gt_i32_e64 s[16:17], 35, v165
	s_and_b64 s[18:19], s[20:21], s[18:19]
	v_cmp_gt_i32_e64 s[14:15], 34, v165
	s_and_b64 s[16:17], s[18:19], s[16:17]
	v_cmp_gt_i32_e64 s[12:13], 33, v165
	s_and_b64 s[14:15], s[16:17], s[14:15]
	v_cmp_gt_i32_e32 vcc, 32, v165
	s_and_b64 s[12:13], s[14:15], s[12:13]
	s_and_b64 vcc, s[12:13], vcc
	v_cndmask_b32_e64 v99, v99, v204, s[72:73]
	v_cndmask_b32_e64 v98, v98, v204, s[70:71]
	v_cndmask_b32_e64 v97, v97, v204, s[68:69]
	v_cndmask_b32_e64 v96, v96, v204, s[66:67]
	v_cndmask_b32_e64 v95, v95, v204, s[64:65]
	v_cndmask_b32_e64 v94, v94, v204, s[62:63]
	v_cndmask_b32_e64 v93, v93, v204, s[60:61]
	v_cndmask_b32_e64 v92, v92, v204, s[58:59]
	v_cndmask_b32_e64 v91, v91, v204, s[56:57]
	v_cndmask_b32_e64 v90, v90, v204, s[54:55]
	v_cndmask_b32_e64 v89, v89, v204, s[52:53]
	v_cndmask_b32_e64 v88, v88, v204, s[50:51]
	v_cndmask_b32_e64 v87, v87, v204, s[48:49]
	v_cndmask_b32_e64 v86, v86, v204, s[46:47]
	v_cndmask_b32_e64 v85, v85, v204, s[44:45]
	v_cndmask_b32_e64 v83, v83, v204, s[42:43]
	v_cndmask_b32_e64 v82, v82, v204, s[40:41]
	v_cndmask_b32_e64 v81, v81, v204, s[38:39]
	v_cndmask_b32_e64 v80, v80, v204, s[36:37]
	v_cndmask_b32_e64 v79, v79, v204, s[34:35]
	v_cndmask_b32_e64 v78, v78, v204, s[30:31]
	v_cndmask_b32_e64 v77, v77, v204, s[28:29]
	v_cndmask_b32_e64 v76, v76, v204, s[26:27]
	v_cndmask_b32_e64 v75, v75, v204, s[24:25]
	v_cndmask_b32_e64 v74, v74, v204, s[22:23]
	v_cndmask_b32_e64 v73, v73, v204, s[20:21]
	v_cndmask_b32_e64 v72, v72, v204, s[18:19]
	v_cndmask_b32_e64 v71, v71, v204, s[16:17]
	v_cndmask_b32_e64 v70, v70, v204, s[14:15]
	v_cndmask_b32_e64 v69, v69, v204, s[12:13]
	v_cndmask_b32_e32 v68, v68, v204, vcc

.Lfa_a_2:
	v_mov_b32_e32 v243, v83
	v_exp_f32_e32 v166, v84
	v_exp_f32_e32 v85, v85
	v_exp_f32_e32 v86, v86
	v_exp_f32_e32 v87, v87
	v_exp_f32_e32 v88, v88
	v_exp_f32_e32 v89, v89
	v_exp_f32_e32 v90, v90
	v_exp_f32_e32 v167, v91
	v_add_f32_e32 v83, 0, v166
	v_add_f32_e32 v83, v85, v83
	v_add_f32_e32 v83, v86, v83
	v_add_f32_e32 v83, v87, v83
	v_cvt_pk_bf16_f32 v168, v166, v85
	v_cvt_pk_bf16_f32 v169, v86, v87
	v_cvt_pk_bf16_f32 v170, v88, v89
	v_cvt_pk_bf16_f32 v171, v90, v167
	v_exp_f32_e32 v91, v92
	v_exp_f32_e32 v92, v93
	s_waitcnt lgkmcnt(0)
	v_mfma_f32_32x32x16_bf16 v[52:67], v[168:171], v[144:147], v[52:67]
	v_mfma_f32_32x32x16_bf16 v[36:51], v[168:171], v[128:131], v[36:51]
	v_mfma_f32_32x32x16_bf16 v[20:35], v[168:171], v[206:209], v[20:35]
	v_mfma_f32_32x32x16_bf16 v[4:19], v[168:171], v[228:231], v[4:19]
	v_exp_f32_e32 v93, v94
	v_exp_f32_e32 v94, v95
	v_exp_f32_e32 v95, v96
	v_exp_f32_e32 v96, v97
	v_exp_f32_e32 v97, v98
	v_exp_f32_e32 v98, v99
	v_add_f32_e32 v83, v88, v83
	v_add_f32_e32 v83, v89, v83
	v_add_f32_e32 v83, v90, v83
	v_add_f32_e32 v83, v167, v83
	v_add_f32_e32 v83, v91, v83
	v_add_f32_e32 v83, v92, v83
	v_add_f32_e32 v83, v93, v83
	v_add_f32_e32 v83, v94, v83
	v_cvt_pk_bf16_f32 v86, v91, v92
	v_cvt_pk_bf16_f32 v87, v93, v94
	v_cvt_pk_bf16_f32 v88, v95, v96
	v_cvt_pk_bf16_f32 v89, v97, v98
	v_exp_f32_e32 v68, v68
	v_exp_f32_e32 v69, v69
	v_mfma_f32_32x32x16_bf16 v[52:67], v[86:89], v[140:143], v[52:67]
	v_mfma_f32_32x32x16_bf16 v[36:51], v[86:89], v[124:127], v[36:51]
	v_mfma_f32_32x32x16_bf16 v[20:35], v[86:89], v[212:215], v[20:35]
	v_mfma_f32_32x32x16_bf16 v[4:19], v[86:89], v[232:235], v[4:19]
	v_exp_f32_e32 v70, v70
	v_exp_f32_e32 v71, v71
	v_exp_f32_e32 v72, v72
	v_exp_f32_e32 v73, v73
	v_exp_f32_e32 v74, v74
	v_exp_f32_e32 v84, v75
	v_add_f32_e32 v83, v95, v83
	v_add_f32_e32 v83, v96, v83
	v_add_f32_e32 v83, v97, v83
	v_add_f32_e32 v83, v98, v83
	v_add_f32_e32 v83, v68, v83
	v_add_f32_e32 v83, v69, v83
	v_add_f32_e32 v83, v70, v83
	v_add_f32_e32 v83, v71, v83
	v_cvt_pk_bf16_f32 v68, v68, v69
	v_cvt_pk_bf16_f32 v69, v70, v71
	v_cvt_pk_bf16_f32 v70, v72, v73
	v_cvt_pk_bf16_f32 v71, v74, v84
	v_exp_f32_e32 v75, v76
	v_exp_f32_e32 v76, v77
	v_mfma_f32_32x32x16_bf16 v[52:67], v[68:71], v[136:139], v[52:67]
	v_mfma_f32_32x32x16_bf16 v[36:51], v[68:71], v[120:123], v[36:51]
	v_mfma_f32_32x32x16_bf16 v[20:35], v[68:71], v[220:223], v[20:35]
	v_mfma_f32_32x32x16_bf16 v[4:19], v[68:71], v[236:239], v[4:19]
	v_exp_f32_e32 v77, v78
	v_exp_f32_e32 v78, v79
	v_exp_f32_e32 v79, v80
	v_exp_f32_e32 v80, v81
	v_exp_f32_e32 v81, v82
	v_exp_f32_e32 v82, v243
	v_add_f32_e32 v83, v72, v83
	v_add_f32_e32 v83, v73, v83
	v_add_f32_e32 v83, v74, v83
	v_add_f32_e32 v83, v84, v83
	v_add_f32_e32 v83, v75, v83
	v_add_f32_e32 v83, v76, v83
	v_add_f32_e32 v83, v77, v83
	v_add_f32_e32 v83, v78, v83
	v_add_f32_e32 v83, v79, v83
	v_add_f32_e32 v83, v80, v83
	v_add_f32_e32 v83, v81, v83
	v_add_f32_e32 v83, v82, v83
	v_cvt_pk_bf16_f32 v72, v75, v76
	v_cvt_pk_bf16_f32 v73, v77, v78
	v_cvt_pk_bf16_f32 v74, v79, v80
	v_cvt_pk_bf16_f32 v75, v81, v82
	v_mov_b32_e32 v99, v83
	s_nop 1
	v_permlane32_swap_b32_e32 v83, v99
	v_mfma_f32_32x32x16_bf16 v[52:67], v[72:75], v[132:135], v[52:67]
	v_mfma_f32_32x32x16_bf16 v[36:51], v[72:75], v[116:119], v[36:51]
	v_mfma_f32_32x32x16_bf16 v[20:35], v[72:75], v[224:227], v[20:35]
	v_mfma_f32_32x32x16_bf16 v[4:19], v[72:75], v[248:251], v[4:19]
	v_add_f32_e32 v99, v83, v99
	v_fmac_f32_e32 v99, v163, v165
	v_mov_b32_e32 v163, v99
	s_branch .LBB0_942

	.amdhsa_kernel _Z8mega_fwd4Args
		.amdhsa_group_segment_fixed_size 0
		.amdhsa_private_segment_fixed_size 0
		.amdhsa_kernarg_size 552
		.amdhsa_user_sgpr_count 2
		.amdhsa_user_sgpr_dispatch_ptr 0
		.amdhsa_user_sgpr_queue_ptr 0
		.amdhsa_user_sgpr_kernarg_segment_ptr 1
		.amdhsa_user_sgpr_dispatch_id 0
		.amdhsa_user_sgpr_kernarg_preload_length 0
		.amdhsa_user_sgpr_kernarg_preload_offset 0
		.amdhsa_user_sgpr_private_segment_size 0
		.amdhsa_uses_dynamic_stack 0
		.amdhsa_enable_private_segment 0
		.amdhsa_system_sgpr_workgroup_id_x 1
		.amdhsa_system_sgpr_workgroup_id_y 0
		.amdhsa_system_sgpr_workgroup_id_z 0
		.amdhsa_system_sgpr_workgroup_info 0
		.amdhsa_system_vgpr_workitem_id 0
		.amdhsa_next_free_vgpr 256
		.amdhsa_next_free_sgpr 102
		.amdhsa_accum_offset 256
		.amdhsa_reserve_vcc 1
		.amdhsa_float_round_mode_32 0
		.amdhsa_float_round_mode_16_64 0
		.amdhsa_float_denorm_mode_32 3
		.amdhsa_float_denorm_mode_16_64 3
		.amdhsa_dx10_clamp 1
		.amdhsa_ieee_mode 1
		.amdhsa_fp16_overflow 0
		.amdhsa_tg_split 0
		.amdhsa_exception_fp_ieee_invalid_op 0
		.amdhsa_exception_fp_denorm_src 0
		.amdhsa_exception_fp_ieee_div_zero 0
		.amdhsa_exception_fp_ieee_overflow 0
		.amdhsa_exception_fp_ieee_underflow 0
		.amdhsa_exception_fp_ieee_inexact 0
		.amdhsa_exception_int_div_zero 0
	.end_amdhsa_kernel

amdhsa.kernels:
  - .agpr_count:     0
    .args:
      - .offset:         0
        .size:           296
        .value_kind:     by_value
      - .offset:         296
        .size:           4
        .value_kind:     hidden_block_count_x
      - .offset:         300
        .size:           4
        .value_kind:     hidden_block_count_y
      - .offset:         304
        .size:           4
        .value_kind:     hidden_block_count_z
      - .offset:         308
        .size:           2
        .value_kind:     hidden_group_size_x
      - .offset:         310
        .size:           2
        .value_kind:     hidden_group_size_y
      - .offset:         312
        .size:           2
        .value_kind:     hidden_group_size_z
      - .offset:         314
        .size:           2
        .value_kind:     hidden_remainder_x
      - .offset:         316
        .size:           2
        .value_kind:     hidden_remainder_y
      - .offset:         318
        .size:           2
        .value_kind:     hidden_remainder_z
      - .offset:         336
        .size:           8
        .value_kind:     hidden_global_offset_x
      - .offset:         344
        .size:           8
        .value_kind:     hidden_global_offset_y
      - .offset:         352
        .size:           8
        .value_kind:     hidden_global_offset_z
      - .offset:         360
        .size:           2
        .value_kind:     hidden_grid_dims
      - .offset:         416
        .size:           4
        .value_kind:     hidden_dynamic_lds_size
    .group_segment_fixed_size: 0
    .kernarg_segment_align: 8
    .kernarg_segment_size: 552
    .language:       OpenCL C
    .language_version:
      - 2
      - 0
    .max_flat_workgroup_size: 512
    .name:           _Z8mega_fwd4Args
    .private_segment_fixed_size: 0
    .sgpr_count:     108
    .sgpr_spill_count: 76
    .symbol:         _Z8mega_fwd4Args.kd
    .uniform_work_group_size: 1
    .uses_dynamic_stack: false
    .vgpr_count:     256
    .vgpr_spill_count: 0
    .wavefront_size: 64
